# GEMM K-loops: remaining B-operand LDS-DMA address adds removed in 6 of 8 loops by stepping the SGPR base in two stages (+0x80 then +0x40000)
# baseline (speedup 1.0000x reference)
; #define PG8_STAGE(bufoff, gbase, voff) do { _Pragma("unroll") for (int _i = 0; _i < 2; ++_i) \
;         __builtin_amdgcn_global_load_lds((const unsigned*)((const char*)(gbase) + (voff)[_i]), (LAS unsigned*)(lds + (bufoff) + ldsw + _i * 8192), 16, 0, 0); } while (0)
; #define PG8_LDA(dst, b, h) do { _Pragma("unroll") for (int m = 0; m < 4; ++m) _Pragma("unroll") for (int k = 0; k < 2; ++k) dst[m][k] = *(const LAS bf16x8*)(lds + PG8_SA(b, h) + aoff + m * 2048 + k * 1024); } while (0)
; #define PG8_LDB(dst, b, h) do { _Pragma("unroll") for (int n = 0; n < 2; ++n) _Pragma("unroll") for (int k = 0; k < 2; ++k) dst[n][k] = *(const LAS bf16x8*)(lds + PG8_SB(b, h) + boff + n * 2048 + k * 1024); } while (0)
; #define PG8_MMA(ai, bj, At, Bt) do { __builtin_amdgcn_s_setprio(1); _Pragma("unroll") for (int m = 0; m < 4; ++m) _Pragma("unroll") for (int n = 0; n < 2; ++n) _Pragma("unroll") for (int k = 0; k < 2; ++k) \
;         acc[ai][bj][m][n] = __builtin_amdgcn_mfma_f32_16x16x32_bf16(Bt[n][k], At[m][k], acc[ai][bj][m][n], 0, 0, 0); __builtin_amdgcn_s_setprio(0); } while (0)
; #define PG8_WAIT_V(n) asm volatile("s_waitcnt vmcnt(" #n ")" ::: "memory")
; #define PG8_WAIT_L(n) asm volatile("s_waitcnt lgkmcnt(" #n ")" ::: "memory")
; #define PG8_BAR __builtin_amdgcn_s_barrier()
; #define PG8_SCHED __builtin_amdgcn_sched_barrier(0)
; template <class Epi, class Sched>
; DI void gemm_phase(LAS unsigned char* lds, const int K, const Sched& S, const Epi& E) {
;     ...
;         for (int t = 0; t < nt; t += 2) {
;             const bool last = (t == nt - 2);
;             const char* a1 = cA + (size_t)(t + 1) * kstep;
;             const char* a2 = last ? nA : cA + (size_t)(t + 2) * kstep; const char* b2 = last ? nB : cB + (size_t)(t + 2) * kstep;
;             const char* a3 = a2 + kstep; const char* b3 = b2 + kstep;
;             PG8_LDB(B0, 0, 0); PG8_LDB(B1, 0, 1); PG8_SCHED; PG8_LDA(At, 0, 0); PG8_STAGE(PG8_SA(1, 1), a1 + hstep, voffA);
;             PG8_WAIT_V(8); PG8_WAIT_L(0); PG8_BAR; PG8_MMA(0, 0, At, B0); PG8_MMA(0, 1, At, B1); PG8_BAR; PG8_SCHED;
;             PG8_LDA(At, 0, 1); PG8_STAGE(PG8_SB(0, 0), b2, voffB); PG8_STAGE(PG8_SB(0, 1), b2 + hstep, voffB); PG8_STAGE(PG8_SA(0, 0), a2, voffA);
;             PG8_WAIT_V(8); PG8_WAIT_L(0); PG8_BAR; PG8_MMA(1, 0, At, B0); PG8_MMA(1, 1, At, B1); PG8_BAR; PG8_SCHED;
.LBB0_218:
	s_add_u32 s80, s78, 0xfffc0080
	s_addc_u32 s81, s79, -1
	s_add_i32 vcc_lo, 0, 0x10000
	s_cmp_eq_u32 s87, 12
	s_cselect_b32 s83, s45, s81
	s_cselect_b32 s82, s73, s80
	s_cselect_b32 s81, s77, s86
	s_cselect_b32 s80, s84, s85
	s_add_i32 s63, 0, 0x14000
	v_add_u32_e32 v142, vcc_lo, v201
	v_add_u32_e32 v158, s63, v201
	ds_read_b128 v[130:133], v142
	ds_read_b128 v[134:137], v142 offset:1024
	ds_read_b128 v[138:141], v142 offset:2048
	ds_read_b128 v[142:145], v142 offset:3072
	ds_read_b128 v[146:149], v158
	ds_read_b128 v[150:153], v158 offset:1024
	ds_read_b128 v[154:157], v158 offset:2048
	ds_read_b128 v[158:161], v158 offset:3072
	s_nop 0
	s_add_i32 m0, s56, 0xc000
	ds_read_b128 v[174:177], v202
	ds_read_b128 v[182:185], v202 offset:1024
	ds_read_b128 v[190:193], v202 offset:2048
	ds_read_b128 v[194:197], v202 offset:3072
	ds_read_b128 v[212:215], v202 offset:4096
	ds_read_b128 v[216:219], v202 offset:5120
	ds_read_b128 v[220:223], v202 offset:6144
	ds_read_b128 v[224:227], v202 offset:7168
	global_load_lds_dwordx4 v172, s[78:79]
	s_nop 0
	s_add_i32 m0, s56, 0xe000
	s_nop 0
	global_load_lds_dwordx4 v170, s[78:79]
	s_waitcnt vmcnt(8)
	s_waitcnt lgkmcnt(0)
	s_barrier
	s_nop 0
	s_waitcnt lgkmcnt(0)
	v_mfma_f32_16x16x32_bf16 v[126:129], v[130:133], v[174:177], v[126:129]
	v_mfma_f32_16x16x32_bf16 v[122:125], v[138:141], v[174:177], v[122:125]
	v_mfma_f32_16x16x32_bf16 v[110:113], v[130:133], v[190:193], v[110:113]
	v_mfma_f32_16x16x32_bf16 v[106:109], v[138:141], v[190:193], v[106:109]
	v_mfma_f32_16x16x32_bf16 v[94:97], v[130:133], v[212:215], v[94:97]
	v_mfma_f32_16x16x32_bf16 v[90:93], v[138:141], v[212:215], v[90:93]
	v_mfma_f32_16x16x32_bf16 v[78:81], v[130:133], v[220:223], v[78:81]
	v_mfma_f32_16x16x32_bf16 v[74:77], v[138:141], v[220:223], v[74:77]
	v_mfma_f32_16x16x32_bf16 v[126:129], v[134:137], v[182:185], v[126:129]
	v_mfma_f32_16x16x32_bf16 v[122:125], v[142:145], v[182:185], v[122:125]
	v_mfma_f32_16x16x32_bf16 v[110:113], v[134:137], v[194:197], v[110:113]
	v_mfma_f32_16x16x32_bf16 v[106:109], v[142:145], v[194:197], v[106:109]
	v_mfma_f32_16x16x32_bf16 v[94:97], v[134:137], v[216:219], v[94:97]
	v_mfma_f32_16x16x32_bf16 v[90:93], v[142:145], v[216:219], v[90:93]
	v_mfma_f32_16x16x32_bf16 v[78:81], v[134:137], v[224:227], v[78:81]
	v_mfma_f32_16x16x32_bf16 v[74:77], v[142:145], v[224:227], v[74:77]
	s_nop 0
	s_nop 0
	v_mfma_f32_16x16x32_bf16 v[118:121], v[146:149], v[174:177], v[118:121]
	v_mfma_f32_16x16x32_bf16 v[114:117], v[154:157], v[174:177], v[114:117]
	v_mfma_f32_16x16x32_bf16 v[102:105], v[146:149], v[190:193], v[102:105]
	v_mfma_f32_16x16x32_bf16 v[98:101], v[154:157], v[190:193], v[98:101]
	v_mfma_f32_16x16x32_bf16 v[86:89], v[146:149], v[212:215], v[86:89]
	v_mfma_f32_16x16x32_bf16 v[82:85], v[154:157], v[212:215], v[82:85]
	v_mfma_f32_16x16x32_bf16 v[70:73], v[146:149], v[220:223], v[70:73]
	v_mfma_f32_16x16x32_bf16 v[66:69], v[154:157], v[220:223], v[66:69]
	v_mfma_f32_16x16x32_bf16 v[118:121], v[150:153], v[182:185], v[118:121]
	v_mfma_f32_16x16x32_bf16 v[114:117], v[158:161], v[182:185], v[114:117]
	v_mfma_f32_16x16x32_bf16 v[102:105], v[150:153], v[194:197], v[102:105]
	v_mfma_f32_16x16x32_bf16 v[98:101], v[158:161], v[194:197], v[98:101]
	v_mfma_f32_16x16x32_bf16 v[86:89], v[150:153], v[216:219], v[86:89]
	v_mfma_f32_16x16x32_bf16 v[82:85], v[158:161], v[216:219], v[82:85]
	v_mfma_f32_16x16x32_bf16 v[70:73], v[150:153], v[224:227], v[70:73]
	v_mfma_f32_16x16x32_bf16 v[66:69], v[158:161], v[224:227], v[66:69]
	s_nop 0
	s_barrier
	s_add_i32 vcc_lo, vcc_lo, s55
	s_nop 0
	s_mov_b32 m0, vcc_lo
	ds_read_b128 v[174:177], v202 offset:16384
	ds_read_b128 v[182:185], v202 offset:17408
	ds_read_b128 v[190:193], v202 offset:18432
	ds_read_b128 v[194:197], v202 offset:19456
	ds_read_b128 v[212:215], v202 offset:20480
	ds_read_b128 v[216:219], v202 offset:21504
	ds_read_b128 v[220:223], v202 offset:22528
	ds_read_b128 v[224:227], v202 offset:23552
	global_load_lds_dwordx4 v164, s[80:81]
	s_add_i32 m0, vcc_lo, 0x2000
	s_add_u32 vcc_lo, s80, 0x40000
	s_nop 0
	s_addc_u32 vcc_hi, s81, 0
	s_add_i32 s63, s63, s55
	global_load_lds_dwordx4 v168, s[80:81]
	s_nop 0
	s_mov_b32 m0, s63
	s_nop 0
	global_load_lds_dwordx4 v164, vcc
	s_nop 0
	s_add_i32 m0, s63, 0x2000
	s_nop 0
	global_load_lds_dwordx4 v168, vcc
	s_nop 0
	s_add_u32 s98, s82, s90
	s_addc_u32 s99, s83, s91
	s_mov_b32 m0, s56
	s_nop 0
	global_load_lds_dwordx4 v162, s[82:83]
	s_mov_b32 m0, s57
	s_nop 0
	global_load_lds_dwordx4 v166, s[82:83]
	s_waitcnt vmcnt(8)
	s_waitcnt lgkmcnt(0)
	s_barrier
; #define PG8_STAGE(bufoff, gbase, voff) do { _Pragma("unroll") for (int _i = 0; _i < 2; ++_i) \
;         __builtin_amdgcn_global_load_lds((const unsigned*)((const char*)(gbase) + (voff)[_i]), (LAS unsigned*)(lds + (bufoff) + ldsw + _i * 8192), 16, 0, 0); } while (0)
; #define PG8_LDA(dst, b, h) do { _Pragma("unroll") for (int m = 0; m < 4; ++m) _Pragma("unroll") for (int k = 0; k < 2; ++k) dst[m][k] = *(const LAS bf16x8*)(lds + PG8_SA(b, h) + aoff + m * 2048 + k * 1024); } while (0)
; #define PG8_LDB(dst, b, h) do { _Pragma("unroll") for (int n = 0; n < 2; ++n) _Pragma("unroll") for (int k = 0; k < 2; ++k) dst[n][k] = *(const LAS bf16x8*)(lds + PG8_SB(b, h) + boff + n * 2048 + k * 1024); } while (0)
; #define PG8_MMA(ai, bj, At, Bt) do { __builtin_amdgcn_s_setprio(1); _Pragma("unroll") for (int m = 0; m < 4; ++m) _Pragma("unroll") for (int n = 0; n < 2; ++n) _Pragma("unroll") for (int k = 0; k < 2; ++k) \
;         acc[ai][bj][m][n] = __builtin_amdgcn_mfma_f32_16x16x32_bf16(Bt[n][k], At[m][k], acc[ai][bj][m][n], 0, 0, 0); __builtin_amdgcn_s_setprio(0); } while (0)
; #define PG8_WAIT_V(n) asm volatile("s_waitcnt vmcnt(" #n ")" ::: "memory")
; #define PG8_WAIT_L(n) asm volatile("s_waitcnt lgkmcnt(" #n ")" ::: "memory")
; #define PG8_BAR __builtin_amdgcn_s_barrier()
; #define PG8_SCHED __builtin_amdgcn_sched_barrier(0)
; template <class Epi, class Sched>
; DI void gemm_phase(LAS unsigned char* lds, const int K, const Sched& S, const Epi& E) {
;     ...
;             PG8_WAIT_V(8); PG8_WAIT_L(0); PG8_BAR; PG8_MMA(1, 0, At, B0); PG8_MMA(1, 1, At, B1); PG8_BAR; PG8_SCHED;
;             PG8_LDB(B0, 1, 0); PG8_LDB(B1, 1, 1); PG8_SCHED; PG8_LDA(At, 1, 0); PG8_STAGE(PG8_SA(0, 1), a2 + hstep, voffA);
;             PG8_WAIT_V(8); PG8_WAIT_L(0); PG8_BAR; PG8_MMA(0, 0, At, B0); PG8_MMA(0, 1, At, B1); PG8_BAR; PG8_SCHED;
	s_nop 0
	s_waitcnt lgkmcnt(0)
	v_mfma_f32_16x16x32_bf16 v[62:65], v[130:133], v[174:177], v[62:65]
	v_mfma_f32_16x16x32_bf16 v[58:61], v[138:141], v[174:177], v[58:61]
	v_mfma_f32_16x16x32_bf16 v[46:49], v[130:133], v[190:193], v[46:49]
	v_mfma_f32_16x16x32_bf16 v[42:45], v[138:141], v[190:193], v[42:45]
	v_mfma_f32_16x16x32_bf16 v[30:33], v[130:133], v[212:215], v[30:33]
	v_mfma_f32_16x16x32_bf16 v[26:29], v[138:141], v[212:215], v[26:29]
	v_mfma_f32_16x16x32_bf16 v[14:17], v[130:133], v[220:223], v[14:17]
	v_mfma_f32_16x16x32_bf16 v[10:13], v[138:141], v[220:223], v[10:13]
	v_mfma_f32_16x16x32_bf16 v[62:65], v[134:137], v[182:185], v[62:65]
	v_mfma_f32_16x16x32_bf16 v[58:61], v[142:145], v[182:185], v[58:61]
	v_mfma_f32_16x16x32_bf16 v[46:49], v[134:137], v[194:197], v[46:49]
	v_mfma_f32_16x16x32_bf16 v[42:45], v[142:145], v[194:197], v[42:45]
	v_mfma_f32_16x16x32_bf16 v[30:33], v[134:137], v[216:219], v[30:33]
	v_mfma_f32_16x16x32_bf16 v[26:29], v[142:145], v[216:219], v[26:29]
	v_mfma_f32_16x16x32_bf16 v[14:17], v[134:137], v[224:227], v[14:17]
	v_mfma_f32_16x16x32_bf16 v[10:13], v[142:145], v[224:227], v[10:13]
	s_nop 0
	s_nop 0
	v_mfma_f32_16x16x32_bf16 v[54:57], v[146:149], v[174:177], v[54:57]
	v_mfma_f32_16x16x32_bf16 v[50:53], v[154:157], v[174:177], v[50:53]
	v_mfma_f32_16x16x32_bf16 v[38:41], v[146:149], v[190:193], v[38:41]
	v_mfma_f32_16x16x32_bf16 v[34:37], v[154:157], v[190:193], v[34:37]
	v_mfma_f32_16x16x32_bf16 v[22:25], v[146:149], v[212:215], v[22:25]
	v_mfma_f32_16x16x32_bf16 v[18:21], v[154:157], v[212:215], v[18:21]
	v_mfma_f32_16x16x32_bf16 v[6:9], v[146:149], v[220:223], v[6:9]
	v_mfma_f32_16x16x32_bf16 v[2:5], v[154:157], v[220:223], v[2:5]
	v_mfma_f32_16x16x32_bf16 v[54:57], v[150:153], v[182:185], v[54:57]
	v_mfma_f32_16x16x32_bf16 v[50:53], v[158:161], v[182:185], v[50:53]
	v_mfma_f32_16x16x32_bf16 v[38:41], v[150:153], v[194:197], v[38:41]
	v_mfma_f32_16x16x32_bf16 v[34:37], v[158:161], v[194:197], v[34:37]
	v_mfma_f32_16x16x32_bf16 v[22:25], v[150:153], v[216:219], v[22:25]
	v_mfma_f32_16x16x32_bf16 v[18:21], v[158:161], v[216:219], v[18:21]
	v_mfma_f32_16x16x32_bf16 v[6:9], v[150:153], v[224:227], v[6:9]
	v_mfma_f32_16x16x32_bf16 v[2:5], v[158:161], v[224:227], v[2:5]
	s_nop 0
	s_barrier
	s_add_i32 s63, 0, 0x18000
	s_add_i32 vcc_lo, 0, 0x1c000
	v_add_u32_e32 v142, s63, v201
	v_add_u32_e32 v158, vcc_lo, v201
	ds_read_b128 v[130:133], v142
	ds_read_b128 v[134:137], v142 offset:1024
	ds_read_b128 v[138:141], v142 offset:2048
	ds_read_b128 v[142:145], v142 offset:3072
	ds_read_b128 v[146:149], v158
	ds_read_b128 v[150:153], v158 offset:1024
	ds_read_b128 v[154:157], v158 offset:2048
	ds_read_b128 v[158:161], v158 offset:3072
	s_add_u32 s82, s82, 0x40000
	s_addc_u32 s83, s83, 0
	s_mov_b32 m0, s58
	s_nop 0
	ds_read_b128 v[174:177], v202 offset:32768
	ds_read_b128 v[182:185], v202 offset:33792
	ds_read_b128 v[190:193], v202 offset:34816
	ds_read_b128 v[194:197], v202 offset:35840
	ds_read_b128 v[212:215], v202 offset:36864
	ds_read_b128 v[216:219], v202 offset:37888
	ds_read_b128 v[220:223], v202 offset:38912
	ds_read_b128 v[224:227], v202 offset:39936
	global_load_lds_dwordx4 v162, s[82:83]
	s_nop 0
	s_mov_b32 m0, s59
	s_nop 0
	global_load_lds_dwordx4 v166, s[82:83]
	s_waitcnt vmcnt(8)
	s_waitcnt lgkmcnt(0)
	s_barrier
	s_nop 0
	s_waitcnt lgkmcnt(0)
	v_mfma_f32_16x16x32_bf16 v[126:129], v[130:133], v[174:177], v[126:129]
	v_mfma_f32_16x16x32_bf16 v[122:125], v[138:141], v[174:177], v[122:125]
	v_mfma_f32_16x16x32_bf16 v[110:113], v[130:133], v[190:193], v[110:113]
	v_mfma_f32_16x16x32_bf16 v[106:109], v[138:141], v[190:193], v[106:109]
	v_mfma_f32_16x16x32_bf16 v[94:97], v[130:133], v[212:215], v[94:97]
	v_mfma_f32_16x16x32_bf16 v[90:93], v[138:141], v[212:215], v[90:93]
	v_mfma_f32_16x16x32_bf16 v[78:81], v[130:133], v[220:223], v[78:81]
	v_mfma_f32_16x16x32_bf16 v[74:77], v[138:141], v[220:223], v[74:77]
	v_mfma_f32_16x16x32_bf16 v[126:129], v[134:137], v[182:185], v[126:129]
	v_mfma_f32_16x16x32_bf16 v[122:125], v[142:145], v[182:185], v[122:125]
	v_mfma_f32_16x16x32_bf16 v[110:113], v[134:137], v[194:197], v[110:113]
	v_mfma_f32_16x16x32_bf16 v[106:109], v[142:145], v[194:197], v[106:109]
	v_mfma_f32_16x16x32_bf16 v[94:97], v[134:137], v[216:219], v[94:97]
	v_mfma_f32_16x16x32_bf16 v[90:93], v[142:145], v[216:219], v[90:93]
	v_mfma_f32_16x16x32_bf16 v[78:81], v[134:137], v[224:227], v[78:81]
	v_mfma_f32_16x16x32_bf16 v[74:77], v[142:145], v[224:227], v[74:77]
	s_nop 0
	s_nop 0
	v_mfma_f32_16x16x32_bf16 v[118:121], v[146:149], v[174:177], v[118:121]
	v_mfma_f32_16x16x32_bf16 v[114:117], v[154:157], v[174:177], v[114:117]
	v_mfma_f32_16x16x32_bf16 v[102:105], v[146:149], v[190:193], v[102:105]
	v_mfma_f32_16x16x32_bf16 v[98:101], v[154:157], v[190:193], v[98:101]
	v_mfma_f32_16x16x32_bf16 v[86:89], v[146:149], v[212:215], v[86:89]
	v_mfma_f32_16x16x32_bf16 v[82:85], v[154:157], v[212:215], v[82:85]
	v_mfma_f32_16x16x32_bf16 v[70:73], v[146:149], v[220:223], v[70:73]
	v_mfma_f32_16x16x32_bf16 v[66:69], v[154:157], v[220:223], v[66:69]
	v_mfma_f32_16x16x32_bf16 v[118:121], v[150:153], v[182:185], v[118:121]
	v_mfma_f32_16x16x32_bf16 v[114:117], v[158:161], v[182:185], v[114:117]
	v_mfma_f32_16x16x32_bf16 v[102:105], v[150:153], v[194:197], v[102:105]
	v_mfma_f32_16x16x32_bf16 v[98:101], v[158:161], v[194:197], v[98:101]
	v_mfma_f32_16x16x32_bf16 v[86:89], v[150:153], v[216:219], v[86:89]
	v_mfma_f32_16x16x32_bf16 v[82:85], v[158:161], v[216:219], v[82:85]
	v_mfma_f32_16x16x32_bf16 v[70:73], v[150:153], v[224:227], v[70:73]
	v_mfma_f32_16x16x32_bf16 v[66:69], v[158:161], v[224:227], v[66:69]
	s_nop 0
	s_barrier
; #define PG8_STAGE(bufoff, gbase, voff) do { _Pragma("unroll") for (int _i = 0; _i < 2; ++_i) \
;         __builtin_amdgcn_global_load_lds((const unsigned*)((const char*)(gbase) + (voff)[_i]), (LAS unsigned*)(lds + (bufoff) + ldsw + _i * 8192), 16, 0, 0); } while (0)
; #define PG8_LDA(dst, b, h) do { _Pragma("unroll") for (int m = 0; m < 4; ++m) _Pragma("unroll") for (int k = 0; k < 2; ++k) dst[m][k] = *(const LAS bf16x8*)(lds + PG8_SA(b, h) + aoff + m * 2048 + k * 1024); } while (0)
; #define PG8_MMA(ai, bj, At, Bt) do { __builtin_amdgcn_s_setprio(1); _Pragma("unroll") for (int m = 0; m < 4; ++m) _Pragma("unroll") for (int n = 0; n < 2; ++n) _Pragma("unroll") for (int k = 0; k < 2; ++k) \
;         acc[ai][bj][m][n] = __builtin_amdgcn_mfma_f32_16x16x32_bf16(Bt[n][k], At[m][k], acc[ai][bj][m][n], 0, 0, 0); __builtin_amdgcn_s_setprio(0); } while (0)
; #define PG8_WAIT_V(n) asm volatile("s_waitcnt vmcnt(" #n ")" ::: "memory")
; #define PG8_WAIT_L(n) asm volatile("s_waitcnt lgkmcnt(" #n ")" ::: "memory")
; #define PG8_BAR __builtin_amdgcn_s_barrier()
; #define PG8_SCHED __builtin_amdgcn_sched_barrier(0)
; template <class Epi, class Sched>
; DI void gemm_phase(LAS unsigned char* lds, const int K, const Sched& S, const Epi& E) {
;     ...
;             PG8_LDA(At, 1, 1); PG8_STAGE(PG8_SB(1, 0), b3, voffB); PG8_STAGE(PG8_SB(1, 1), b3 + hstep, voffB); PG8_STAGE(PG8_SA(1, 0), a3, voffA);
;             PG8_WAIT_V(8); PG8_WAIT_L(0); PG8_BAR; PG8_MMA(1, 0, At, B0); PG8_MMA(1, 1, At, B1); PG8_BAR; PG8_SCHED;
;         }
;         if (wr == 0) PG8_BAR;
	s_add_i32 s63, s63, s55
	s_add_u32 s80, s80, 0x80
	s_addc_u32 s81, s81, 0
	s_mov_b32 m0, s63
	ds_read_b128 v[174:177], v202 offset:49152
	ds_read_b128 v[182:185], v202 offset:50176
	ds_read_b128 v[190:193], v202 offset:51200
	ds_read_b128 v[194:197], v202 offset:52224
	ds_read_b128 v[212:215], v202 offset:53248
	ds_read_b128 v[216:219], v202 offset:54272
	ds_read_b128 v[220:223], v202 offset:55296
	ds_read_b128 v[224:227], v202 offset:56320
	global_load_lds_dwordx4 v164, s[80:81]
	s_add_i32 m0, s63, 0x2000
	s_nop 0
	s_nop 0
	s_nop 0
	s_add_i32 s63, vcc_lo, s55
	global_load_lds_dwordx4 v168, s[80:81]
	s_add_u32 s80, s80, 0x40000
	s_addc_u32 s81, s81, 0
	s_nop 0
	s_mov_b32 m0, s63
	s_nop 0
	global_load_lds_dwordx4 v164, s[80:81]
	s_nop 0
	s_add_i32 m0, s63, 0x2000
	s_nop 0
	global_load_lds_dwordx4 v168, s[80:81]
	s_nop 0
	s_mov_b32 m0, s47
	s_nop 0
	global_load_lds_dwordx4 v162, s[98:99]
	s_nop 0
	s_mov_b32 m0, s62
	s_nop 0
	global_load_lds_dwordx4 v166, s[98:99]
	s_waitcnt vmcnt(8)
	s_waitcnt lgkmcnt(0)
	s_barrier
	s_nop 0
	s_waitcnt lgkmcnt(0)
	v_mfma_f32_16x16x32_bf16 v[62:65], v[130:133], v[174:177], v[62:65]
	v_mfma_f32_16x16x32_bf16 v[58:61], v[138:141], v[174:177], v[58:61]
	v_mfma_f32_16x16x32_bf16 v[46:49], v[130:133], v[190:193], v[46:49]
	v_mfma_f32_16x16x32_bf16 v[42:45], v[138:141], v[190:193], v[42:45]
	v_mfma_f32_16x16x32_bf16 v[30:33], v[130:133], v[212:215], v[30:33]
	v_mfma_f32_16x16x32_bf16 v[26:29], v[138:141], v[212:215], v[26:29]
	v_mfma_f32_16x16x32_bf16 v[14:17], v[130:133], v[220:223], v[14:17]
	v_mfma_f32_16x16x32_bf16 v[10:13], v[138:141], v[220:223], v[10:13]
	v_mfma_f32_16x16x32_bf16 v[62:65], v[134:137], v[182:185], v[62:65]
	v_mfma_f32_16x16x32_bf16 v[58:61], v[142:145], v[182:185], v[58:61]
	v_mfma_f32_16x16x32_bf16 v[46:49], v[134:137], v[194:197], v[46:49]
	v_mfma_f32_16x16x32_bf16 v[42:45], v[142:145], v[194:197], v[42:45]
	v_mfma_f32_16x16x32_bf16 v[30:33], v[134:137], v[216:219], v[30:33]
	v_mfma_f32_16x16x32_bf16 v[26:29], v[142:145], v[216:219], v[26:29]
	v_mfma_f32_16x16x32_bf16 v[14:17], v[134:137], v[224:227], v[14:17]
	v_mfma_f32_16x16x32_bf16 v[10:13], v[142:145], v[224:227], v[10:13]
	s_nop 0
	s_nop 0
	v_mfma_f32_16x16x32_bf16 v[54:57], v[146:149], v[174:177], v[54:57]
	v_mfma_f32_16x16x32_bf16 v[50:53], v[154:157], v[174:177], v[50:53]
	v_mfma_f32_16x16x32_bf16 v[38:41], v[146:149], v[190:193], v[38:41]
	v_mfma_f32_16x16x32_bf16 v[34:37], v[154:157], v[190:193], v[34:37]
	v_mfma_f32_16x16x32_bf16 v[22:25], v[146:149], v[212:215], v[22:25]
	v_mfma_f32_16x16x32_bf16 v[18:21], v[154:157], v[212:215], v[18:21]
	v_mfma_f32_16x16x32_bf16 v[6:9], v[146:149], v[220:223], v[6:9]
	v_mfma_f32_16x16x32_bf16 v[2:5], v[154:157], v[220:223], v[2:5]
	v_mfma_f32_16x16x32_bf16 v[54:57], v[150:153], v[182:185], v[54:57]
	v_mfma_f32_16x16x32_bf16 v[50:53], v[158:161], v[182:185], v[50:53]
	v_mfma_f32_16x16x32_bf16 v[38:41], v[150:153], v[194:197], v[38:41]
	v_mfma_f32_16x16x32_bf16 v[34:37], v[158:161], v[194:197], v[34:37]
	v_mfma_f32_16x16x32_bf16 v[22:25], v[150:153], v[216:219], v[22:25]
	v_mfma_f32_16x16x32_bf16 v[18:21], v[158:161], v[216:219], v[18:21]
	v_mfma_f32_16x16x32_bf16 v[6:9], v[150:153], v[224:227], v[6:9]
	v_mfma_f32_16x16x32_bf16 v[2:5], v[158:161], v[224:227], v[2:5]
	s_nop 0
	s_barrier
	s_add_i32 s87, s87, 2
	s_add_u32 s85, s85, 0x100
	s_addc_u32 s86, s86, 0
	s_add_u32 s78, s78, 0x100
	s_addc_u32 s79, s79, 0
	s_cmp_gt_u32 s87, 13
	s_cbranch_scc0 .LBB0_218
	s_and_b64 vcc, exec, s[50:51]
	s_cbranch_vccz .LBB0_221
	s_barrier

; #define PG8_STAGE(bufoff, gbase, voff) do { _Pragma("unroll") for (int _i = 0; _i < 2; ++_i) \
;         __builtin_amdgcn_global_load_lds((const unsigned*)((const char*)(gbase) + (voff)[_i]), (LAS unsigned*)(lds + (bufoff) + ldsw + _i * 8192), 16, 0, 0); } while (0)
; #define PG8_LDA(dst, b, h) do { _Pragma("unroll") for (int m = 0; m < 4; ++m) _Pragma("unroll") for (int k = 0; k < 2; ++k) dst[m][k] = *(const LAS bf16x8*)(lds + PG8_SA(b, h) + aoff + m * 2048 + k * 1024); } while (0)
; #define PG8_LDB(dst, b, h) do { _Pragma("unroll") for (int n = 0; n < 2; ++n) _Pragma("unroll") for (int k = 0; k < 2; ++k) dst[n][k] = *(const LAS bf16x8*)(lds + PG8_SB(b, h) + boff + n * 2048 + k * 1024); } while (0)
; #define PG8_MMA(ai, bj, At, Bt) do { __builtin_amdgcn_s_setprio(1); _Pragma("unroll") for (int m = 0; m < 4; ++m) _Pragma("unroll") for (int n = 0; n < 2; ++n) _Pragma("unroll") for (int k = 0; k < 2; ++k) \
;         acc[ai][bj][m][n] = __builtin_amdgcn_mfma_f32_16x16x32_bf16(Bt[n][k], At[m][k], acc[ai][bj][m][n], 0, 0, 0); __builtin_amdgcn_s_setprio(0); } while (0)
; #define PG8_WAIT_V(n) asm volatile("s_waitcnt vmcnt(" #n ")" ::: "memory")
; #define PG8_WAIT_L(n) asm volatile("s_waitcnt lgkmcnt(" #n ")" ::: "memory")
; #define PG8_BAR __builtin_amdgcn_s_barrier()
; #define PG8_SCHED __builtin_amdgcn_sched_barrier(0)
; template <class Epi, class Sched>
; DI void gemm_phase(LAS unsigned char* lds, const int K, const Sched& S, const Epi& E) {
;     ...
;         for (int t = 0; t < nt; t += 2) {
;             const bool last = (t == nt - 2);
;             const char* a1 = cA + (size_t)(t + 1) * kstep;
;             const char* a2 = last ? nA : cA + (size_t)(t + 2) * kstep; const char* b2 = last ? nB : cB + (size_t)(t + 2) * kstep;
;             const char* a3 = a2 + kstep; const char* b3 = b2 + kstep;
;             PG8_LDB(B0, 0, 0); PG8_LDB(B1, 0, 1); PG8_SCHED; PG8_LDA(At, 0, 0); PG8_STAGE(PG8_SA(1, 1), a1 + hstep, voffA);
;             PG8_WAIT_V(8); PG8_WAIT_L(0); PG8_BAR; PG8_MMA(0, 0, At, B0); PG8_MMA(0, 1, At, B1); PG8_BAR; PG8_SCHED;
;             PG8_LDA(At, 0, 1); PG8_STAGE(PG8_SB(0, 0), b2, voffB); PG8_STAGE(PG8_SB(0, 1), b2 + hstep, voffB); PG8_STAGE(PG8_SA(0, 0), a2, voffA);
;             PG8_WAIT_V(8); PG8_WAIT_L(0); PG8_BAR; PG8_MMA(1, 0, At, B0); PG8_MMA(1, 1, At, B1); PG8_BAR; PG8_SCHED;
.LBB0_338:
	s_add_u32 s58, s56, 0xfffc0080
	s_addc_u32 s59, s57, -1
	s_add_i32 s79, 0, 0x10000
	s_cmp_eq_u32 s78, 12
	s_cselect_b32 s61, s53, s59
	s_cselect_b32 s60, s52, s58
	v_add_u32_e32 v142, s79, v145
	s_cselect_b32 s59, s55, s51
	s_cselect_b32 s58, s54, s49
	s_add_i32 s82, 0, 0x14000
	ds_read_b128 v[148:151], v142
	ds_read_b128 v[152:155], v142 offset:1024
	ds_read_b128 v[156:159], v142 offset:2048
	ds_read_b128 v[160:163], v142 offset:3072
	v_add_u32_e32 v142, s82, v145
	ds_read_b128 v[164:167], v142
	ds_read_b128 v[168:171], v142 offset:1024
	ds_read_b128 v[172:175], v142 offset:2048
	ds_read_b128 v[182:185], v142 offset:3072
	s_nop 0
	s_add_i32 m0, s67, 0xc000
	ds_read_b128 v[190:193], v146
	ds_read_b128 v[194:197], v146 offset:1024
	ds_read_b128 v[198:201], v146 offset:2048
	ds_read_b128 v[202:205], v146 offset:3072
	ds_read_b128 v[212:215], v146 offset:4096
	ds_read_b128 v[216:219], v146 offset:5120
	ds_read_b128 v[220:223], v146 offset:6144
	ds_read_b128 v[224:227], v146 offset:7168
	global_load_lds_dwordx4 v140, s[56:57]
	s_nop 0
	s_add_i32 m0, s67, 0xe000
	s_nop 0
	global_load_lds_dwordx4 v138, s[56:57]
	s_waitcnt vmcnt(8)
	s_waitcnt lgkmcnt(0)
	s_barrier
	s_nop 0
	s_waitcnt lgkmcnt(0)
	v_mfma_f32_16x16x32_bf16 v[126:129], v[148:151], v[190:193], v[126:129]
	v_mfma_f32_16x16x32_bf16 v[122:125], v[156:159], v[190:193], v[122:125]
	v_mfma_f32_16x16x32_bf16 v[110:113], v[148:151], v[198:201], v[110:113]
	v_mfma_f32_16x16x32_bf16 v[106:109], v[156:159], v[198:201], v[106:109]
	v_mfma_f32_16x16x32_bf16 v[94:97], v[148:151], v[212:215], v[94:97]
	v_mfma_f32_16x16x32_bf16 v[90:93], v[156:159], v[212:215], v[90:93]
	v_mfma_f32_16x16x32_bf16 v[78:81], v[148:151], v[220:223], v[78:81]
	v_mfma_f32_16x16x32_bf16 v[74:77], v[156:159], v[220:223], v[74:77]
	v_mfma_f32_16x16x32_bf16 v[126:129], v[152:155], v[194:197], v[126:129]
	v_mfma_f32_16x16x32_bf16 v[122:125], v[160:163], v[194:197], v[122:125]
	v_mfma_f32_16x16x32_bf16 v[110:113], v[152:155], v[202:205], v[110:113]
	v_mfma_f32_16x16x32_bf16 v[106:109], v[160:163], v[202:205], v[106:109]
	v_mfma_f32_16x16x32_bf16 v[94:97], v[152:155], v[216:219], v[94:97]
	v_mfma_f32_16x16x32_bf16 v[90:93], v[160:163], v[216:219], v[90:93]
	v_mfma_f32_16x16x32_bf16 v[78:81], v[152:155], v[224:227], v[78:81]
	v_mfma_f32_16x16x32_bf16 v[74:77], v[160:163], v[224:227], v[74:77]
	s_nop 0
	s_nop 0
	v_mfma_f32_16x16x32_bf16 v[118:121], v[164:167], v[190:193], v[118:121]
	v_mfma_f32_16x16x32_bf16 v[114:117], v[172:175], v[190:193], v[114:117]
	v_mfma_f32_16x16x32_bf16 v[102:105], v[164:167], v[198:201], v[102:105]
	v_mfma_f32_16x16x32_bf16 v[98:101], v[172:175], v[198:201], v[98:101]
	v_mfma_f32_16x16x32_bf16 v[86:89], v[164:167], v[212:215], v[86:89]
	v_mfma_f32_16x16x32_bf16 v[82:85], v[172:175], v[212:215], v[82:85]
	v_mfma_f32_16x16x32_bf16 v[70:73], v[164:167], v[220:223], v[70:73]
	v_mfma_f32_16x16x32_bf16 v[66:69], v[172:175], v[220:223], v[66:69]
	v_mfma_f32_16x16x32_bf16 v[118:121], v[168:171], v[194:197], v[118:121]
	v_mfma_f32_16x16x32_bf16 v[114:117], v[182:185], v[194:197], v[114:117]
	v_mfma_f32_16x16x32_bf16 v[102:105], v[168:171], v[202:205], v[102:105]
	v_mfma_f32_16x16x32_bf16 v[98:101], v[182:185], v[202:205], v[98:101]
	v_mfma_f32_16x16x32_bf16 v[86:89], v[168:171], v[216:219], v[86:89]
	v_mfma_f32_16x16x32_bf16 v[82:85], v[182:185], v[216:219], v[82:85]
	v_mfma_f32_16x16x32_bf16 v[70:73], v[168:171], v[224:227], v[70:73]
	v_mfma_f32_16x16x32_bf16 v[66:69], v[182:185], v[224:227], v[66:69]
	s_nop 0
	s_barrier
	s_add_i32 s79, s79, s66
	s_nop 0
	s_mov_b32 m0, s79
	ds_read_b128 v[190:193], v146 offset:16384
	ds_read_b128 v[194:197], v146 offset:17408
	ds_read_b128 v[198:201], v146 offset:18432
	ds_read_b128 v[202:205], v146 offset:19456
	ds_read_b128 v[212:215], v146 offset:20480
	ds_read_b128 v[216:219], v146 offset:21504
	ds_read_b128 v[220:223], v146 offset:22528
	ds_read_b128 v[224:227], v146 offset:23552
	global_load_lds_dwordx4 v134, s[58:59]
	s_add_i32 m0, s79, 0x2000
	s_add_u32 s80, s58, 0x40000
	s_nop 0
	s_addc_u32 s81, s59, 0
	s_add_i32 s79, s82, s66
	global_load_lds_dwordx4 v130, s[58:59]
	s_nop 0
	s_mov_b32 m0, s79
	s_nop 0
	global_load_lds_dwordx4 v134, s[80:81]
	s_nop 0
	s_add_i32 m0, s79, 0x2000
	s_nop 0
	global_load_lds_dwordx4 v130, s[80:81]
	s_nop 0
	s_add_u32 s98, s60, s90
	s_addc_u32 s99, s61, s91
	s_mov_b32 m0, s67
	s_nop 0
	global_load_lds_dwordx4 v136, s[60:61]
	s_mov_b32 m0, s68
	s_nop 0
	global_load_lds_dwordx4 v132, s[60:61]
	s_waitcnt vmcnt(8)
	s_waitcnt lgkmcnt(0)
	s_barrier
; #define PG8_STAGE(bufoff, gbase, voff) do { _Pragma("unroll") for (int _i = 0; _i < 2; ++_i) \
;         __builtin_amdgcn_global_load_lds((const unsigned*)((const char*)(gbase) + (voff)[_i]), (LAS unsigned*)(lds + (bufoff) + ldsw + _i * 8192), 16, 0, 0); } while (0)
; #define PG8_LDA(dst, b, h) do { _Pragma("unroll") for (int m = 0; m < 4; ++m) _Pragma("unroll") for (int k = 0; k < 2; ++k) dst[m][k] = *(const LAS bf16x8*)(lds + PG8_SA(b, h) + aoff + m * 2048 + k * 1024); } while (0)
; #define PG8_LDB(dst, b, h) do { _Pragma("unroll") for (int n = 0; n < 2; ++n) _Pragma("unroll") for (int k = 0; k < 2; ++k) dst[n][k] = *(const LAS bf16x8*)(lds + PG8_SB(b, h) + boff + n * 2048 + k * 1024); } while (0)
; #define PG8_MMA(ai, bj, At, Bt) do { __builtin_amdgcn_s_setprio(1); _Pragma("unroll") for (int m = 0; m < 4; ++m) _Pragma("unroll") for (int n = 0; n < 2; ++n) _Pragma("unroll") for (int k = 0; k < 2; ++k) \
;         acc[ai][bj][m][n] = __builtin_amdgcn_mfma_f32_16x16x32_bf16(Bt[n][k], At[m][k], acc[ai][bj][m][n], 0, 0, 0); __builtin_amdgcn_s_setprio(0); } while (0)
; #define PG8_WAIT_V(n) asm volatile("s_waitcnt vmcnt(" #n ")" ::: "memory")
; #define PG8_WAIT_L(n) asm volatile("s_waitcnt lgkmcnt(" #n ")" ::: "memory")
; #define PG8_BAR __builtin_amdgcn_s_barrier()
; #define PG8_SCHED __builtin_amdgcn_sched_barrier(0)
; template <class Epi, class Sched>
; DI void gemm_phase(LAS unsigned char* lds, const int K, const Sched& S, const Epi& E) {
;     ...
;             PG8_WAIT_V(8); PG8_WAIT_L(0); PG8_BAR; PG8_MMA(1, 0, At, B0); PG8_MMA(1, 1, At, B1); PG8_BAR; PG8_SCHED;
;             PG8_LDB(B0, 1, 0); PG8_LDB(B1, 1, 1); PG8_SCHED; PG8_LDA(At, 1, 0); PG8_STAGE(PG8_SA(0, 1), a2 + hstep, voffA);
;             PG8_WAIT_V(8); PG8_WAIT_L(0); PG8_BAR; PG8_MMA(0, 0, At, B0); PG8_MMA(0, 1, At, B1); PG8_BAR; PG8_SCHED;
	s_nop 0
	s_waitcnt lgkmcnt(0)
	v_mfma_f32_16x16x32_bf16 v[62:65], v[148:151], v[190:193], v[62:65]
	v_mfma_f32_16x16x32_bf16 v[58:61], v[156:159], v[190:193], v[58:61]
	v_mfma_f32_16x16x32_bf16 v[46:49], v[148:151], v[198:201], v[46:49]
	v_mfma_f32_16x16x32_bf16 v[42:45], v[156:159], v[198:201], v[42:45]
	v_mfma_f32_16x16x32_bf16 v[30:33], v[148:151], v[212:215], v[30:33]
	v_mfma_f32_16x16x32_bf16 v[26:29], v[156:159], v[212:215], v[26:29]
	v_mfma_f32_16x16x32_bf16 v[14:17], v[148:151], v[220:223], v[14:17]
	v_mfma_f32_16x16x32_bf16 v[10:13], v[156:159], v[220:223], v[10:13]
	v_mfma_f32_16x16x32_bf16 v[62:65], v[152:155], v[194:197], v[62:65]
	v_mfma_f32_16x16x32_bf16 v[58:61], v[160:163], v[194:197], v[58:61]
	v_mfma_f32_16x16x32_bf16 v[46:49], v[152:155], v[202:205], v[46:49]
	v_mfma_f32_16x16x32_bf16 v[42:45], v[160:163], v[202:205], v[42:45]
	v_mfma_f32_16x16x32_bf16 v[30:33], v[152:155], v[216:219], v[30:33]
	v_mfma_f32_16x16x32_bf16 v[26:29], v[160:163], v[216:219], v[26:29]
	v_mfma_f32_16x16x32_bf16 v[14:17], v[152:155], v[224:227], v[14:17]
	v_mfma_f32_16x16x32_bf16 v[10:13], v[160:163], v[224:227], v[10:13]
	s_nop 0
	s_nop 0
	v_mfma_f32_16x16x32_bf16 v[54:57], v[164:167], v[190:193], v[54:57]
	v_mfma_f32_16x16x32_bf16 v[50:53], v[172:175], v[190:193], v[50:53]
	v_mfma_f32_16x16x32_bf16 v[38:41], v[164:167], v[198:201], v[38:41]
	v_mfma_f32_16x16x32_bf16 v[34:37], v[172:175], v[198:201], v[34:37]
	v_mfma_f32_16x16x32_bf16 v[22:25], v[164:167], v[212:215], v[22:25]
	v_mfma_f32_16x16x32_bf16 v[18:21], v[172:175], v[212:215], v[18:21]
	v_mfma_f32_16x16x32_bf16 v[6:9], v[164:167], v[220:223], v[6:9]
	v_mfma_f32_16x16x32_bf16 v[2:5], v[172:175], v[220:223], v[2:5]
	v_mfma_f32_16x16x32_bf16 v[54:57], v[168:171], v[194:197], v[54:57]
	v_mfma_f32_16x16x32_bf16 v[50:53], v[182:185], v[194:197], v[50:53]
	v_mfma_f32_16x16x32_bf16 v[38:41], v[168:171], v[202:205], v[38:41]
	v_mfma_f32_16x16x32_bf16 v[34:37], v[182:185], v[202:205], v[34:37]
	v_mfma_f32_16x16x32_bf16 v[22:25], v[168:171], v[216:219], v[22:25]
	v_mfma_f32_16x16x32_bf16 v[18:21], v[182:185], v[216:219], v[18:21]
	v_mfma_f32_16x16x32_bf16 v[6:9], v[168:171], v[224:227], v[6:9]
	v_mfma_f32_16x16x32_bf16 v[2:5], v[182:185], v[224:227], v[2:5]
	s_nop 0
	s_barrier
	s_add_i32 s79, 0, 0x18000
	v_add_u32_e32 v147, s79, v145
	s_add_i32 s80, 0, 0x1c000
	ds_read_b128 v[148:151], v147
	ds_read_b128 v[152:155], v147 offset:1024
	ds_read_b128 v[156:159], v147 offset:2048
	ds_read_b128 v[160:163], v147 offset:3072
	v_add_u32_e32 v147, s80, v145
	ds_read_b128 v[164:167], v147
	ds_read_b128 v[168:171], v147 offset:1024
	ds_read_b128 v[172:175], v147 offset:2048
	ds_read_b128 v[182:185], v147 offset:3072
	s_add_u32 s60, s60, 0x40000
	s_addc_u32 s61, s61, 0
	s_mov_b32 m0, s69
	s_nop 0
	ds_read_b128 v[190:193], v146 offset:32768
	ds_read_b128 v[194:197], v146 offset:33792
	ds_read_b128 v[198:201], v146 offset:34816
	ds_read_b128 v[202:205], v146 offset:35840
	ds_read_b128 v[212:215], v146 offset:36864
	ds_read_b128 v[216:219], v146 offset:37888
	ds_read_b128 v[220:223], v146 offset:38912
	ds_read_b128 v[224:227], v146 offset:39936
	global_load_lds_dwordx4 v136, s[60:61]
	s_nop 0
	s_mov_b32 m0, s70
	s_nop 0
	global_load_lds_dwordx4 v132, s[60:61]
	s_waitcnt vmcnt(8)
	s_waitcnt lgkmcnt(0)
	s_barrier
	s_nop 0
	s_waitcnt lgkmcnt(0)
	v_mfma_f32_16x16x32_bf16 v[126:129], v[148:151], v[190:193], v[126:129]
	v_mfma_f32_16x16x32_bf16 v[122:125], v[156:159], v[190:193], v[122:125]
	v_mfma_f32_16x16x32_bf16 v[110:113], v[148:151], v[198:201], v[110:113]
	v_mfma_f32_16x16x32_bf16 v[106:109], v[156:159], v[198:201], v[106:109]
	v_mfma_f32_16x16x32_bf16 v[94:97], v[148:151], v[212:215], v[94:97]
	v_mfma_f32_16x16x32_bf16 v[90:93], v[156:159], v[212:215], v[90:93]
	v_mfma_f32_16x16x32_bf16 v[78:81], v[148:151], v[220:223], v[78:81]
	v_mfma_f32_16x16x32_bf16 v[74:77], v[156:159], v[220:223], v[74:77]
	v_mfma_f32_16x16x32_bf16 v[126:129], v[152:155], v[194:197], v[126:129]
	v_mfma_f32_16x16x32_bf16 v[122:125], v[160:163], v[194:197], v[122:125]
	v_mfma_f32_16x16x32_bf16 v[110:113], v[152:155], v[202:205], v[110:113]
	v_mfma_f32_16x16x32_bf16 v[106:109], v[160:163], v[202:205], v[106:109]
	v_mfma_f32_16x16x32_bf16 v[94:97], v[152:155], v[216:219], v[94:97]
	v_mfma_f32_16x16x32_bf16 v[90:93], v[160:163], v[216:219], v[90:93]
	v_mfma_f32_16x16x32_bf16 v[78:81], v[152:155], v[224:227], v[78:81]
	v_mfma_f32_16x16x32_bf16 v[74:77], v[160:163], v[224:227], v[74:77]
	s_nop 0
	s_nop 0
	v_mfma_f32_16x16x32_bf16 v[118:121], v[164:167], v[190:193], v[118:121]
	v_mfma_f32_16x16x32_bf16 v[114:117], v[172:175], v[190:193], v[114:117]
	v_mfma_f32_16x16x32_bf16 v[102:105], v[164:167], v[198:201], v[102:105]
	v_mfma_f32_16x16x32_bf16 v[98:101], v[172:175], v[198:201], v[98:101]
	v_mfma_f32_16x16x32_bf16 v[86:89], v[164:167], v[212:215], v[86:89]
	v_mfma_f32_16x16x32_bf16 v[82:85], v[172:175], v[212:215], v[82:85]
	v_mfma_f32_16x16x32_bf16 v[70:73], v[164:167], v[220:223], v[70:73]
	v_mfma_f32_16x16x32_bf16 v[66:69], v[172:175], v[220:223], v[66:69]
	v_mfma_f32_16x16x32_bf16 v[118:121], v[168:171], v[194:197], v[118:121]
	v_mfma_f32_16x16x32_bf16 v[114:117], v[182:185], v[194:197], v[114:117]
	v_mfma_f32_16x16x32_bf16 v[102:105], v[168:171], v[202:205], v[102:105]
	v_mfma_f32_16x16x32_bf16 v[98:101], v[182:185], v[202:205], v[98:101]
	v_mfma_f32_16x16x32_bf16 v[86:89], v[168:171], v[216:219], v[86:89]
	v_mfma_f32_16x16x32_bf16 v[82:85], v[182:185], v[216:219], v[82:85]
	v_mfma_f32_16x16x32_bf16 v[70:73], v[168:171], v[224:227], v[70:73]
	v_mfma_f32_16x16x32_bf16 v[66:69], v[182:185], v[224:227], v[66:69]
	s_nop 0
	s_barrier
; #define PG8_STAGE(bufoff, gbase, voff) do { _Pragma("unroll") for (int _i = 0; _i < 2; ++_i) \
;         __builtin_amdgcn_global_load_lds((const unsigned*)((const char*)(gbase) + (voff)[_i]), (LAS unsigned*)(lds + (bufoff) + ldsw + _i * 8192), 16, 0, 0); } while (0)
; #define PG8_LDA(dst, b, h) do { _Pragma("unroll") for (int m = 0; m < 4; ++m) _Pragma("unroll") for (int k = 0; k < 2; ++k) dst[m][k] = *(const LAS bf16x8*)(lds + PG8_SA(b, h) + aoff + m * 2048 + k * 1024); } while (0)
; #define PG8_MMA(ai, bj, At, Bt) do { __builtin_amdgcn_s_setprio(1); _Pragma("unroll") for (int m = 0; m < 4; ++m) _Pragma("unroll") for (int n = 0; n < 2; ++n) _Pragma("unroll") for (int k = 0; k < 2; ++k) \
;         acc[ai][bj][m][n] = __builtin_amdgcn_mfma_f32_16x16x32_bf16(Bt[n][k], At[m][k], acc[ai][bj][m][n], 0, 0, 0); __builtin_amdgcn_s_setprio(0); } while (0)
; #define PG8_WAIT_V(n) asm volatile("s_waitcnt vmcnt(" #n ")" ::: "memory")
; #define PG8_WAIT_L(n) asm volatile("s_waitcnt lgkmcnt(" #n ")" ::: "memory")
; #define PG8_BAR __builtin_amdgcn_s_barrier()
; #define PG8_SCHED __builtin_amdgcn_sched_barrier(0)
; template <class Epi, class Sched>
; DI void gemm_phase(LAS unsigned char* lds, const int K, const Sched& S, const Epi& E) {
;     ...
;             PG8_LDA(At, 1, 1); PG8_STAGE(PG8_SB(1, 0), b3, voffB); PG8_STAGE(PG8_SB(1, 1), b3 + hstep, voffB); PG8_STAGE(PG8_SA(1, 0), a3, voffA);
;             PG8_WAIT_V(8); PG8_WAIT_L(0); PG8_BAR; PG8_MMA(1, 0, At, B0); PG8_MMA(1, 1, At, B1); PG8_BAR; PG8_SCHED;
;         }
;         if (wr == 0) PG8_BAR;
	s_add_i32 s60, s79, s66
	s_add_u32 s58, s58, 0x80
	s_addc_u32 s59, s59, 0
	s_mov_b32 m0, s60
	ds_read_b128 v[190:193], v146 offset:49152
	ds_read_b128 v[194:197], v146 offset:50176
	ds_read_b128 v[198:201], v146 offset:51200
	ds_read_b128 v[202:205], v146 offset:52224
	ds_read_b128 v[212:215], v146 offset:53248
	ds_read_b128 v[216:219], v146 offset:54272
	ds_read_b128 v[220:223], v146 offset:55296
	ds_read_b128 v[224:227], v146 offset:56320
	global_load_lds_dwordx4 v134, s[58:59]
	s_add_i32 m0, s60, 0x2000
	s_nop 0
	s_nop 0
	s_nop 0
	s_add_i32 s60, s80, s66
	global_load_lds_dwordx4 v130, s[58:59]
	s_add_u32 s58, s58, 0x40000
	s_addc_u32 s59, s59, 0
	s_nop 0
	s_mov_b32 m0, s60
	s_nop 0
	global_load_lds_dwordx4 v134, s[58:59]
	s_nop 0
	s_add_i32 m0, s60, 0x2000
	s_nop 0
	global_load_lds_dwordx4 v130, s[58:59]
	s_nop 0
	s_mov_b32 m0, s73
	s_nop 0
	global_load_lds_dwordx4 v136, s[98:99]
	s_nop 0
	s_mov_b32 m0, s74
	s_nop 0
	global_load_lds_dwordx4 v132, s[98:99]
	s_waitcnt vmcnt(8)
	s_waitcnt lgkmcnt(0)
	s_barrier
	s_nop 0
	s_waitcnt lgkmcnt(0)
	v_mfma_f32_16x16x32_bf16 v[62:65], v[148:151], v[190:193], v[62:65]
	v_mfma_f32_16x16x32_bf16 v[58:61], v[156:159], v[190:193], v[58:61]
	v_mfma_f32_16x16x32_bf16 v[46:49], v[148:151], v[198:201], v[46:49]
	v_mfma_f32_16x16x32_bf16 v[42:45], v[156:159], v[198:201], v[42:45]
	v_mfma_f32_16x16x32_bf16 v[30:33], v[148:151], v[212:215], v[30:33]
	v_mfma_f32_16x16x32_bf16 v[26:29], v[156:159], v[212:215], v[26:29]
	v_mfma_f32_16x16x32_bf16 v[14:17], v[148:151], v[220:223], v[14:17]
	v_mfma_f32_16x16x32_bf16 v[10:13], v[156:159], v[220:223], v[10:13]
	v_mfma_f32_16x16x32_bf16 v[62:65], v[152:155], v[194:197], v[62:65]
	v_mfma_f32_16x16x32_bf16 v[58:61], v[160:163], v[194:197], v[58:61]
	v_mfma_f32_16x16x32_bf16 v[46:49], v[152:155], v[202:205], v[46:49]
	v_mfma_f32_16x16x32_bf16 v[42:45], v[160:163], v[202:205], v[42:45]
	v_mfma_f32_16x16x32_bf16 v[30:33], v[152:155], v[216:219], v[30:33]
	v_mfma_f32_16x16x32_bf16 v[26:29], v[160:163], v[216:219], v[26:29]
	v_mfma_f32_16x16x32_bf16 v[14:17], v[152:155], v[224:227], v[14:17]
	v_mfma_f32_16x16x32_bf16 v[10:13], v[160:163], v[224:227], v[10:13]
	s_nop 0
	s_nop 0
	v_mfma_f32_16x16x32_bf16 v[54:57], v[164:167], v[190:193], v[54:57]
	v_mfma_f32_16x16x32_bf16 v[50:53], v[172:175], v[190:193], v[50:53]
	v_mfma_f32_16x16x32_bf16 v[38:41], v[164:167], v[198:201], v[38:41]
	v_mfma_f32_16x16x32_bf16 v[34:37], v[172:175], v[198:201], v[34:37]
	v_mfma_f32_16x16x32_bf16 v[22:25], v[164:167], v[212:215], v[22:25]
	v_mfma_f32_16x16x32_bf16 v[18:21], v[172:175], v[212:215], v[18:21]
	v_mfma_f32_16x16x32_bf16 v[6:9], v[164:167], v[220:223], v[6:9]
	v_mfma_f32_16x16x32_bf16 v[2:5], v[172:175], v[220:223], v[2:5]
	v_mfma_f32_16x16x32_bf16 v[54:57], v[168:171], v[194:197], v[54:57]
	v_mfma_f32_16x16x32_bf16 v[50:53], v[182:185], v[194:197], v[50:53]
	v_mfma_f32_16x16x32_bf16 v[38:41], v[168:171], v[202:205], v[38:41]
	v_mfma_f32_16x16x32_bf16 v[34:37], v[182:185], v[202:205], v[34:37]
	v_mfma_f32_16x16x32_bf16 v[22:25], v[168:171], v[216:219], v[22:25]
	v_mfma_f32_16x16x32_bf16 v[18:21], v[182:185], v[216:219], v[18:21]
	v_mfma_f32_16x16x32_bf16 v[6:9], v[168:171], v[224:227], v[6:9]
	v_mfma_f32_16x16x32_bf16 v[2:5], v[182:185], v[224:227], v[2:5]
	s_nop 0
	s_barrier
	s_add_i32 s78, s78, 2
	s_add_u32 s49, s49, 0x100
	s_addc_u32 s51, s51, 0
	s_add_u32 s56, s56, 0x100
	s_addc_u32 s57, s57, 0
	s_cmp_gt_u32 s78, 13
	s_cbranch_scc0 .LBB0_338
	s_and_b64 vcc, exec, s[44:45]
	s_cbranch_vccz .LBB0_341
	s_barrier

; #define PG8_STAGE(bufoff, gbase, voff) do { _Pragma("unroll") for (int _i = 0; _i < 2; ++_i) \
;         __builtin_amdgcn_global_load_lds((const unsigned*)((const char*)(gbase) + (voff)[_i]), (LAS unsigned*)(lds + (bufoff) + ldsw + _i * 8192), 16, 0, 0); } while (0)
; #define PG8_LDA(dst, b, h) do { _Pragma("unroll") for (int m = 0; m < 4; ++m) _Pragma("unroll") for (int k = 0; k < 2; ++k) dst[m][k] = *(const LAS bf16x8*)(lds + PG8_SA(b, h) + aoff + m * 2048 + k * 1024); } while (0)
; #define PG8_LDB(dst, b, h) do { _Pragma("unroll") for (int n = 0; n < 2; ++n) _Pragma("unroll") for (int k = 0; k < 2; ++k) dst[n][k] = *(const LAS bf16x8*)(lds + PG8_SB(b, h) + boff + n * 2048 + k * 1024); } while (0)
; #define PG8_MMA(ai, bj, At, Bt) do { __builtin_amdgcn_s_setprio(1); _Pragma("unroll") for (int m = 0; m < 4; ++m) _Pragma("unroll") for (int n = 0; n < 2; ++n) _Pragma("unroll") for (int k = 0; k < 2; ++k) \
;         acc[ai][bj][m][n] = __builtin_amdgcn_mfma_f32_16x16x32_bf16(Bt[n][k], At[m][k], acc[ai][bj][m][n], 0, 0, 0); __builtin_amdgcn_s_setprio(0); } while (0)
; #define PG8_WAIT_V(n) asm volatile("s_waitcnt vmcnt(" #n ")" ::: "memory")
; #define PG8_WAIT_L(n) asm volatile("s_waitcnt lgkmcnt(" #n ")" ::: "memory")
; #define PG8_BAR __builtin_amdgcn_s_barrier()
; #define PG8_SCHED __builtin_amdgcn_sched_barrier(0)
; template <class Epi, class Sched>
; DI void gemm_phase(LAS unsigned char* lds, const int K, const Sched& S, const Epi& E) {
;     ...
;             const bool last = (t == nt - 2);
;             const char* a1 = cA + (size_t)(t + 1) * kstep;
;             const char* a2 = last ? nA : cA + (size_t)(t + 2) * kstep; const char* b2 = last ? nB : cB + (size_t)(t + 2) * kstep;
;             const char* a3 = a2 + kstep; const char* b3 = b2 + kstep;
;             PG8_LDB(B0, 0, 0); PG8_LDB(B1, 0, 1); PG8_SCHED; PG8_LDA(At, 0, 0); PG8_STAGE(PG8_SA(1, 1), a1 + hstep, voffA);
;             PG8_WAIT_V(8); PG8_WAIT_L(0); PG8_BAR; PG8_MMA(0, 0, At, B0); PG8_MMA(0, 1, At, B1); PG8_BAR; PG8_SCHED;
;             PG8_LDA(At, 0, 1); PG8_STAGE(PG8_SB(0, 0), b2, voffB); PG8_STAGE(PG8_SB(0, 1), b2 + hstep, voffB); PG8_STAGE(PG8_SA(0, 0), a2, voffA);
;             PG8_WAIT_V(8); PG8_WAIT_L(0); PG8_BAR; PG8_MMA(1, 0, At, B0); PG8_MMA(1, 1, At, B1); PG8_BAR; PG8_SCHED;
.LBB0_465:
	s_add_u32 s70, s68, 0xfffc0080
	s_addc_u32 s71, s69, -1
	s_add_i32 vcc_lo, 0, 0x10000
	s_cmp_eq_u32 s79, 12
	s_cselect_b32 s73, s65, s71
	s_cselect_b32 s72, s67, s70
	s_cselect_b32 s71, s74, s78
	s_cselect_b32 s70, s76, s77
	s_add_i32 s42, 0, 0x14000
	v_add_u32_e32 v142, vcc_lo, v203
	v_add_u32_e32 v158, s42, v203
	ds_read_b128 v[130:133], v142
	ds_read_b128 v[134:137], v142 offset:1024
	ds_read_b128 v[138:141], v142 offset:2048
	ds_read_b128 v[142:145], v142 offset:3072
	ds_read_b128 v[146:149], v158
	ds_read_b128 v[150:153], v158 offset:1024
	ds_read_b128 v[154:157], v158 offset:2048
	ds_read_b128 v[158:161], v158 offset:3072
	s_nop 0
	s_add_i32 m0, s86, 0xc000
	ds_read_b128 v[174:177], v204
	ds_read_b128 v[182:185], v204 offset:1024
	ds_read_b128 v[190:193], v204 offset:2048
	ds_read_b128 v[194:197], v204 offset:3072
	ds_read_b128 v[198:201], v204 offset:4096
	ds_read_b128 v[212:215], v204 offset:5120
	ds_read_b128 v[216:219], v204 offset:6144
	ds_read_b128 v[220:223], v204 offset:7168
	global_load_lds_dwordx4 v172, s[68:69]
	s_nop 0
	s_add_i32 m0, s86, 0xe000
	s_nop 0
	global_load_lds_dwordx4 v170, s[68:69]
	s_waitcnt vmcnt(8)
	s_waitcnt lgkmcnt(0)
	s_barrier
	s_nop 0
	s_waitcnt lgkmcnt(0)
	v_mfma_f32_16x16x32_bf16 v[126:129], v[130:133], v[174:177], v[126:129]
	v_mfma_f32_16x16x32_bf16 v[122:125], v[138:141], v[174:177], v[122:125]
	v_mfma_f32_16x16x32_bf16 v[110:113], v[130:133], v[190:193], v[110:113]
	v_mfma_f32_16x16x32_bf16 v[106:109], v[138:141], v[190:193], v[106:109]
	v_mfma_f32_16x16x32_bf16 v[94:97], v[130:133], v[198:201], v[94:97]
	v_mfma_f32_16x16x32_bf16 v[90:93], v[138:141], v[198:201], v[90:93]
	v_mfma_f32_16x16x32_bf16 v[78:81], v[130:133], v[216:219], v[78:81]
	v_mfma_f32_16x16x32_bf16 v[74:77], v[138:141], v[216:219], v[74:77]
	v_mfma_f32_16x16x32_bf16 v[126:129], v[134:137], v[182:185], v[126:129]
	v_mfma_f32_16x16x32_bf16 v[122:125], v[142:145], v[182:185], v[122:125]
	v_mfma_f32_16x16x32_bf16 v[110:113], v[134:137], v[194:197], v[110:113]
	v_mfma_f32_16x16x32_bf16 v[106:109], v[142:145], v[194:197], v[106:109]
	v_mfma_f32_16x16x32_bf16 v[94:97], v[134:137], v[212:215], v[94:97]
	v_mfma_f32_16x16x32_bf16 v[90:93], v[142:145], v[212:215], v[90:93]
	v_mfma_f32_16x16x32_bf16 v[78:81], v[134:137], v[220:223], v[78:81]
	v_mfma_f32_16x16x32_bf16 v[74:77], v[142:145], v[220:223], v[74:77]
	s_nop 0
	s_nop 0
	v_mfma_f32_16x16x32_bf16 v[118:121], v[146:149], v[174:177], v[118:121]
	v_mfma_f32_16x16x32_bf16 v[114:117], v[154:157], v[174:177], v[114:117]
	v_mfma_f32_16x16x32_bf16 v[102:105], v[146:149], v[190:193], v[102:105]
	v_mfma_f32_16x16x32_bf16 v[98:101], v[154:157], v[190:193], v[98:101]
	v_mfma_f32_16x16x32_bf16 v[86:89], v[146:149], v[198:201], v[86:89]
	v_mfma_f32_16x16x32_bf16 v[82:85], v[154:157], v[198:201], v[82:85]
	v_mfma_f32_16x16x32_bf16 v[70:73], v[146:149], v[216:219], v[70:73]
	v_mfma_f32_16x16x32_bf16 v[66:69], v[154:157], v[216:219], v[66:69]
	v_mfma_f32_16x16x32_bf16 v[118:121], v[150:153], v[182:185], v[118:121]
	v_mfma_f32_16x16x32_bf16 v[114:117], v[158:161], v[182:185], v[114:117]
	v_mfma_f32_16x16x32_bf16 v[102:105], v[150:153], v[194:197], v[102:105]
	v_mfma_f32_16x16x32_bf16 v[98:101], v[158:161], v[194:197], v[98:101]
	v_mfma_f32_16x16x32_bf16 v[86:89], v[150:153], v[212:215], v[86:89]
	v_mfma_f32_16x16x32_bf16 v[82:85], v[158:161], v[212:215], v[82:85]
	v_mfma_f32_16x16x32_bf16 v[70:73], v[150:153], v[220:223], v[70:73]
	v_mfma_f32_16x16x32_bf16 v[66:69], v[158:161], v[220:223], v[66:69]
	s_nop 0
	s_barrier
	s_add_i32 s43, vcc_lo, s85
	s_nop 0
	s_mov_b32 m0, s43
	ds_read_b128 v[174:177], v204 offset:16384
	ds_read_b128 v[182:185], v204 offset:17408
	ds_read_b128 v[190:193], v204 offset:18432
	ds_read_b128 v[194:197], v204 offset:19456
	ds_read_b128 v[198:201], v204 offset:20480
	ds_read_b128 v[212:215], v204 offset:21504
	ds_read_b128 v[216:219], v204 offset:22528
	ds_read_b128 v[220:223], v204 offset:23552
	global_load_lds_dwordx4 v164, s[70:71]
	s_add_i32 m0, s43, 0x2000
	s_add_u32 vcc_lo, s70, 0x40000
	s_nop 0
	s_addc_u32 vcc_hi, s71, 0
	s_add_i32 s42, s42, s85
	global_load_lds_dwordx4 v168, s[70:71]
	s_nop 0
	s_mov_b32 m0, s42
	s_nop 0
	global_load_lds_dwordx4 v164, vcc
	s_nop 0
	s_add_i32 m0, s42, 0x2000
	s_nop 0
	global_load_lds_dwordx4 v168, vcc
	s_nop 0
	s_add_u32 s98, s72, s90
	s_addc_u32 s99, s73, s91
	s_mov_b32 m0, s86
	s_nop 0
	global_load_lds_dwordx4 v162, s[72:73]
	s_mov_b32 m0, s87
	s_nop 0
	global_load_lds_dwordx4 v166, s[72:73]
	s_waitcnt vmcnt(8)
	s_waitcnt lgkmcnt(0)
	s_barrier
; #define PG8_STAGE(bufoff, gbase, voff) do { _Pragma("unroll") for (int _i = 0; _i < 2; ++_i) \
;         __builtin_amdgcn_global_load_lds((const unsigned*)((const char*)(gbase) + (voff)[_i]), (LAS unsigned*)(lds + (bufoff) + ldsw + _i * 8192), 16, 0, 0); } while (0)
; #define PG8_LDA(dst, b, h) do { _Pragma("unroll") for (int m = 0; m < 4; ++m) _Pragma("unroll") for (int k = 0; k < 2; ++k) dst[m][k] = *(const LAS bf16x8*)(lds + PG8_SA(b, h) + aoff + m * 2048 + k * 1024); } while (0)
; #define PG8_LDB(dst, b, h) do { _Pragma("unroll") for (int n = 0; n < 2; ++n) _Pragma("unroll") for (int k = 0; k < 2; ++k) dst[n][k] = *(const LAS bf16x8*)(lds + PG8_SB(b, h) + boff + n * 2048 + k * 1024); } while (0)
; #define PG8_MMA(ai, bj, At, Bt) do { __builtin_amdgcn_s_setprio(1); _Pragma("unroll") for (int m = 0; m < 4; ++m) _Pragma("unroll") for (int n = 0; n < 2; ++n) _Pragma("unroll") for (int k = 0; k < 2; ++k) \
;         acc[ai][bj][m][n] = __builtin_amdgcn_mfma_f32_16x16x32_bf16(Bt[n][k], At[m][k], acc[ai][bj][m][n], 0, 0, 0); __builtin_amdgcn_s_setprio(0); } while (0)
; #define PG8_WAIT_V(n) asm volatile("s_waitcnt vmcnt(" #n ")" ::: "memory")
; #define PG8_WAIT_L(n) asm volatile("s_waitcnt lgkmcnt(" #n ")" ::: "memory")
; #define PG8_BAR __builtin_amdgcn_s_barrier()
; #define PG8_SCHED __builtin_amdgcn_sched_barrier(0)
; template <class Epi, class Sched>
; DI void gemm_phase(LAS unsigned char* lds, const int K, const Sched& S, const Epi& E) {
;     ...
;             PG8_WAIT_V(8); PG8_WAIT_L(0); PG8_BAR; PG8_MMA(1, 0, At, B0); PG8_MMA(1, 1, At, B1); PG8_BAR; PG8_SCHED;
;             PG8_LDB(B0, 1, 0); PG8_LDB(B1, 1, 1); PG8_SCHED; PG8_LDA(At, 1, 0); PG8_STAGE(PG8_SA(0, 1), a2 + hstep, voffA);
;             PG8_WAIT_V(8); PG8_WAIT_L(0); PG8_BAR; PG8_MMA(0, 0, At, B0); PG8_MMA(0, 1, At, B1); PG8_BAR; PG8_SCHED;
	s_nop 0
	s_waitcnt lgkmcnt(0)
	v_mfma_f32_16x16x32_bf16 v[62:65], v[130:133], v[174:177], v[62:65]
	v_mfma_f32_16x16x32_bf16 v[58:61], v[138:141], v[174:177], v[58:61]
	v_mfma_f32_16x16x32_bf16 v[46:49], v[130:133], v[190:193], v[46:49]
	v_mfma_f32_16x16x32_bf16 v[42:45], v[138:141], v[190:193], v[42:45]
	v_mfma_f32_16x16x32_bf16 v[30:33], v[130:133], v[198:201], v[30:33]
	v_mfma_f32_16x16x32_bf16 v[26:29], v[138:141], v[198:201], v[26:29]
	v_mfma_f32_16x16x32_bf16 v[14:17], v[130:133], v[216:219], v[14:17]
	v_mfma_f32_16x16x32_bf16 v[10:13], v[138:141], v[216:219], v[10:13]
	v_mfma_f32_16x16x32_bf16 v[62:65], v[134:137], v[182:185], v[62:65]
	v_mfma_f32_16x16x32_bf16 v[58:61], v[142:145], v[182:185], v[58:61]
	v_mfma_f32_16x16x32_bf16 v[46:49], v[134:137], v[194:197], v[46:49]
	v_mfma_f32_16x16x32_bf16 v[42:45], v[142:145], v[194:197], v[42:45]
	v_mfma_f32_16x16x32_bf16 v[30:33], v[134:137], v[212:215], v[30:33]
	v_mfma_f32_16x16x32_bf16 v[26:29], v[142:145], v[212:215], v[26:29]
	v_mfma_f32_16x16x32_bf16 v[14:17], v[134:137], v[220:223], v[14:17]
	v_mfma_f32_16x16x32_bf16 v[10:13], v[142:145], v[220:223], v[10:13]
	s_nop 0
	s_nop 0
	v_mfma_f32_16x16x32_bf16 v[54:57], v[146:149], v[174:177], v[54:57]
	v_mfma_f32_16x16x32_bf16 v[50:53], v[154:157], v[174:177], v[50:53]
	v_mfma_f32_16x16x32_bf16 v[38:41], v[146:149], v[190:193], v[38:41]
	v_mfma_f32_16x16x32_bf16 v[34:37], v[154:157], v[190:193], v[34:37]
	v_mfma_f32_16x16x32_bf16 v[22:25], v[146:149], v[198:201], v[22:25]
	v_mfma_f32_16x16x32_bf16 v[18:21], v[154:157], v[198:201], v[18:21]
	v_mfma_f32_16x16x32_bf16 v[6:9], v[146:149], v[216:219], v[6:9]
	v_mfma_f32_16x16x32_bf16 v[2:5], v[154:157], v[216:219], v[2:5]
	v_mfma_f32_16x16x32_bf16 v[54:57], v[150:153], v[182:185], v[54:57]
	v_mfma_f32_16x16x32_bf16 v[50:53], v[158:161], v[182:185], v[50:53]
	v_mfma_f32_16x16x32_bf16 v[38:41], v[150:153], v[194:197], v[38:41]
	v_mfma_f32_16x16x32_bf16 v[34:37], v[158:161], v[194:197], v[34:37]
	v_mfma_f32_16x16x32_bf16 v[22:25], v[150:153], v[212:215], v[22:25]
	v_mfma_f32_16x16x32_bf16 v[18:21], v[158:161], v[212:215], v[18:21]
	v_mfma_f32_16x16x32_bf16 v[6:9], v[150:153], v[220:223], v[6:9]
	v_mfma_f32_16x16x32_bf16 v[2:5], v[158:161], v[220:223], v[2:5]
	s_nop 0
	s_barrier
	s_add_i32 s42, 0, 0x18000
	s_add_i32 s43, 0, 0x1c000
	v_add_u32_e32 v142, s42, v203
	v_add_u32_e32 v158, s43, v203
	ds_read_b128 v[130:133], v142
	ds_read_b128 v[134:137], v142 offset:1024
	ds_read_b128 v[138:141], v142 offset:2048
	ds_read_b128 v[142:145], v142 offset:3072
	ds_read_b128 v[146:149], v158
	ds_read_b128 v[150:153], v158 offset:1024
	ds_read_b128 v[154:157], v158 offset:2048
	ds_read_b128 v[158:161], v158 offset:3072
	s_add_u32 s72, s72, 0x40000
	s_addc_u32 s73, s73, 0
	s_mov_b32 m0, s92
	s_nop 0
	ds_read_b128 v[174:177], v204 offset:32768
	ds_read_b128 v[182:185], v204 offset:33792
	ds_read_b128 v[190:193], v204 offset:34816
	ds_read_b128 v[194:197], v204 offset:35840
	ds_read_b128 v[198:201], v204 offset:36864
	ds_read_b128 v[212:215], v204 offset:37888
	ds_read_b128 v[216:219], v204 offset:38912
	ds_read_b128 v[220:223], v204 offset:39936
	global_load_lds_dwordx4 v162, s[72:73]
	s_nop 0
	s_mov_b32 m0, s94
	s_nop 0
	global_load_lds_dwordx4 v166, s[72:73]
	s_waitcnt vmcnt(8)
	s_waitcnt lgkmcnt(0)
	s_barrier
	s_nop 0
	s_waitcnt lgkmcnt(0)
	v_mfma_f32_16x16x32_bf16 v[126:129], v[130:133], v[174:177], v[126:129]
	v_mfma_f32_16x16x32_bf16 v[122:125], v[138:141], v[174:177], v[122:125]
	v_mfma_f32_16x16x32_bf16 v[110:113], v[130:133], v[190:193], v[110:113]
	v_mfma_f32_16x16x32_bf16 v[106:109], v[138:141], v[190:193], v[106:109]
	v_mfma_f32_16x16x32_bf16 v[94:97], v[130:133], v[198:201], v[94:97]
	v_mfma_f32_16x16x32_bf16 v[90:93], v[138:141], v[198:201], v[90:93]
	v_mfma_f32_16x16x32_bf16 v[78:81], v[130:133], v[216:219], v[78:81]
	v_mfma_f32_16x16x32_bf16 v[74:77], v[138:141], v[216:219], v[74:77]
	v_mfma_f32_16x16x32_bf16 v[126:129], v[134:137], v[182:185], v[126:129]
	v_mfma_f32_16x16x32_bf16 v[122:125], v[142:145], v[182:185], v[122:125]
	v_mfma_f32_16x16x32_bf16 v[110:113], v[134:137], v[194:197], v[110:113]
	v_mfma_f32_16x16x32_bf16 v[106:109], v[142:145], v[194:197], v[106:109]
	v_mfma_f32_16x16x32_bf16 v[94:97], v[134:137], v[212:215], v[94:97]
	v_mfma_f32_16x16x32_bf16 v[90:93], v[142:145], v[212:215], v[90:93]
	v_mfma_f32_16x16x32_bf16 v[78:81], v[134:137], v[220:223], v[78:81]
	v_mfma_f32_16x16x32_bf16 v[74:77], v[142:145], v[220:223], v[74:77]
	s_nop 0
	s_nop 0
	v_mfma_f32_16x16x32_bf16 v[118:121], v[146:149], v[174:177], v[118:121]
	v_mfma_f32_16x16x32_bf16 v[114:117], v[154:157], v[174:177], v[114:117]
	v_mfma_f32_16x16x32_bf16 v[102:105], v[146:149], v[190:193], v[102:105]
	v_mfma_f32_16x16x32_bf16 v[98:101], v[154:157], v[190:193], v[98:101]
	v_mfma_f32_16x16x32_bf16 v[86:89], v[146:149], v[198:201], v[86:89]
	v_mfma_f32_16x16x32_bf16 v[82:85], v[154:157], v[198:201], v[82:85]
	v_mfma_f32_16x16x32_bf16 v[70:73], v[146:149], v[216:219], v[70:73]
	v_mfma_f32_16x16x32_bf16 v[66:69], v[154:157], v[216:219], v[66:69]
	v_mfma_f32_16x16x32_bf16 v[118:121], v[150:153], v[182:185], v[118:121]
	v_mfma_f32_16x16x32_bf16 v[114:117], v[158:161], v[182:185], v[114:117]
	v_mfma_f32_16x16x32_bf16 v[102:105], v[150:153], v[194:197], v[102:105]
	v_mfma_f32_16x16x32_bf16 v[98:101], v[158:161], v[194:197], v[98:101]
	v_mfma_f32_16x16x32_bf16 v[86:89], v[150:153], v[212:215], v[86:89]
	v_mfma_f32_16x16x32_bf16 v[82:85], v[158:161], v[212:215], v[82:85]
	v_mfma_f32_16x16x32_bf16 v[70:73], v[150:153], v[220:223], v[70:73]
	v_mfma_f32_16x16x32_bf16 v[66:69], v[158:161], v[220:223], v[66:69]
	s_nop 0
	s_barrier
; #define PG8_STAGE(bufoff, gbase, voff) do { _Pragma("unroll") for (int _i = 0; _i < 2; ++_i) \
;         __builtin_amdgcn_global_load_lds((const unsigned*)((const char*)(gbase) + (voff)[_i]), (LAS unsigned*)(lds + (bufoff) + ldsw + _i * 8192), 16, 0, 0); } while (0)
; #define PG8_LDA(dst, b, h) do { _Pragma("unroll") for (int m = 0; m < 4; ++m) _Pragma("unroll") for (int k = 0; k < 2; ++k) dst[m][k] = *(const LAS bf16x8*)(lds + PG8_SA(b, h) + aoff + m * 2048 + k * 1024); } while (0)
; #define PG8_MMA(ai, bj, At, Bt) do { __builtin_amdgcn_s_setprio(1); _Pragma("unroll") for (int m = 0; m < 4; ++m) _Pragma("unroll") for (int n = 0; n < 2; ++n) _Pragma("unroll") for (int k = 0; k < 2; ++k) \
;         acc[ai][bj][m][n] = __builtin_amdgcn_mfma_f32_16x16x32_bf16(Bt[n][k], At[m][k], acc[ai][bj][m][n], 0, 0, 0); __builtin_amdgcn_s_setprio(0); } while (0)
; #define PG8_WAIT_V(n) asm volatile("s_waitcnt vmcnt(" #n ")" ::: "memory")
; #define PG8_WAIT_L(n) asm volatile("s_waitcnt lgkmcnt(" #n ")" ::: "memory")
; #define PG8_BAR __builtin_amdgcn_s_barrier()
; #define PG8_SCHED __builtin_amdgcn_sched_barrier(0)
; template <class Epi, class Sched>
; DI void gemm_phase(LAS unsigned char* lds, const int K, const Sched& S, const Epi& E) {
;     ...
;             PG8_LDA(At, 1, 1); PG8_STAGE(PG8_SB(1, 0), b3, voffB); PG8_STAGE(PG8_SB(1, 1), b3 + hstep, voffB); PG8_STAGE(PG8_SA(1, 0), a3, voffA);
;             PG8_WAIT_V(8); PG8_WAIT_L(0); PG8_BAR; PG8_MMA(1, 0, At, B0); PG8_MMA(1, 1, At, B1); PG8_BAR; PG8_SCHED;
;         }
;         if (wr == 0) PG8_BAR;
	s_add_i32 s42, s42, s85
	s_add_u32 s70, s70, 0x80
	s_addc_u32 s71, s71, 0
	s_mov_b32 m0, s42
	ds_read_b128 v[174:177], v204 offset:49152
	ds_read_b128 v[182:185], v204 offset:50176
	ds_read_b128 v[190:193], v204 offset:51200
	ds_read_b128 v[194:197], v204 offset:52224
	ds_read_b128 v[198:201], v204 offset:53248
	ds_read_b128 v[212:215], v204 offset:54272
	ds_read_b128 v[216:219], v204 offset:55296
	ds_read_b128 v[220:223], v204 offset:56320
	global_load_lds_dwordx4 v164, s[70:71]
	s_add_i32 m0, s42, 0x2000
	s_nop 0
	s_nop 0
	s_nop 0
	s_add_i32 s42, s43, s85
	global_load_lds_dwordx4 v168, s[70:71]
	s_add_u32 s70, s70, 0x40000
	s_addc_u32 s71, s71, 0
	s_nop 0
	s_mov_b32 m0, s42
	s_nop 0
	global_load_lds_dwordx4 v164, s[70:71]
	s_nop 0
	s_add_i32 m0, s42, 0x2000
	s_nop 0
	global_load_lds_dwordx4 v168, s[70:71]
	s_nop 0
	s_mov_b32 m0, s45
	s_nop 0
	global_load_lds_dwordx4 v162, s[98:99]
	s_nop 0
	s_mov_b32 m0, s50
	s_nop 0
	global_load_lds_dwordx4 v166, s[98:99]
	s_waitcnt vmcnt(8)
	s_waitcnt lgkmcnt(0)
	s_barrier
	s_nop 0
	s_waitcnt lgkmcnt(0)
	v_mfma_f32_16x16x32_bf16 v[62:65], v[130:133], v[174:177], v[62:65]
	v_mfma_f32_16x16x32_bf16 v[58:61], v[138:141], v[174:177], v[58:61]
	v_mfma_f32_16x16x32_bf16 v[46:49], v[130:133], v[190:193], v[46:49]
	v_mfma_f32_16x16x32_bf16 v[42:45], v[138:141], v[190:193], v[42:45]
	v_mfma_f32_16x16x32_bf16 v[30:33], v[130:133], v[198:201], v[30:33]
	v_mfma_f32_16x16x32_bf16 v[26:29], v[138:141], v[198:201], v[26:29]
	v_mfma_f32_16x16x32_bf16 v[14:17], v[130:133], v[216:219], v[14:17]
	v_mfma_f32_16x16x32_bf16 v[10:13], v[138:141], v[216:219], v[10:13]
	v_mfma_f32_16x16x32_bf16 v[62:65], v[134:137], v[182:185], v[62:65]
	v_mfma_f32_16x16x32_bf16 v[58:61], v[142:145], v[182:185], v[58:61]
	v_mfma_f32_16x16x32_bf16 v[46:49], v[134:137], v[194:197], v[46:49]
	v_mfma_f32_16x16x32_bf16 v[42:45], v[142:145], v[194:197], v[42:45]
	v_mfma_f32_16x16x32_bf16 v[30:33], v[134:137], v[212:215], v[30:33]
	v_mfma_f32_16x16x32_bf16 v[26:29], v[142:145], v[212:215], v[26:29]
	v_mfma_f32_16x16x32_bf16 v[14:17], v[134:137], v[220:223], v[14:17]
	v_mfma_f32_16x16x32_bf16 v[10:13], v[142:145], v[220:223], v[10:13]
	s_nop 0
	s_nop 0
	v_mfma_f32_16x16x32_bf16 v[54:57], v[146:149], v[174:177], v[54:57]
	v_mfma_f32_16x16x32_bf16 v[50:53], v[154:157], v[174:177], v[50:53]
	v_mfma_f32_16x16x32_bf16 v[38:41], v[146:149], v[190:193], v[38:41]
	v_mfma_f32_16x16x32_bf16 v[34:37], v[154:157], v[190:193], v[34:37]
	v_mfma_f32_16x16x32_bf16 v[22:25], v[146:149], v[198:201], v[22:25]
	v_mfma_f32_16x16x32_bf16 v[18:21], v[154:157], v[198:201], v[18:21]
	v_mfma_f32_16x16x32_bf16 v[6:9], v[146:149], v[216:219], v[6:9]
	v_mfma_f32_16x16x32_bf16 v[2:5], v[154:157], v[216:219], v[2:5]
	v_mfma_f32_16x16x32_bf16 v[54:57], v[150:153], v[182:185], v[54:57]
	v_mfma_f32_16x16x32_bf16 v[50:53], v[158:161], v[182:185], v[50:53]
	v_mfma_f32_16x16x32_bf16 v[38:41], v[150:153], v[194:197], v[38:41]
	v_mfma_f32_16x16x32_bf16 v[34:37], v[158:161], v[194:197], v[34:37]
	v_mfma_f32_16x16x32_bf16 v[22:25], v[150:153], v[212:215], v[22:25]
	v_mfma_f32_16x16x32_bf16 v[18:21], v[158:161], v[212:215], v[18:21]
	v_mfma_f32_16x16x32_bf16 v[6:9], v[150:153], v[220:223], v[6:9]
	v_mfma_f32_16x16x32_bf16 v[2:5], v[158:161], v[220:223], v[2:5]
	s_nop 0
	s_barrier
	s_add_i32 s79, s79, 2
	s_add_u32 s77, s77, 0x100
	s_addc_u32 s78, s78, 0
	s_add_u32 s68, s68, 0x100
	s_addc_u32 s69, s69, 0
	s_cmp_gt_u32 s79, 13
	s_cbranch_scc0 .LBB0_465
	s_and_b64 vcc, exec, s[48:49]
	s_cbranch_vccz .LBB0_468
	s_barrier

; #define PG8_STAGE(bufoff, gbase, voff) do { _Pragma("unroll") for (int _i = 0; _i < 2; ++_i) \
;         __builtin_amdgcn_global_load_lds((const unsigned*)((const char*)(gbase) + (voff)[_i]), (LAS unsigned*)(lds + (bufoff) + ldsw + _i * 8192), 16, 0, 0); } while (0)
; #define PG8_LDA(dst, b, h) do { _Pragma("unroll") for (int m = 0; m < 4; ++m) _Pragma("unroll") for (int k = 0; k < 2; ++k) dst[m][k] = *(const LAS bf16x8*)(lds + PG8_SA(b, h) + aoff + m * 2048 + k * 1024); } while (0)
; #define PG8_LDB(dst, b, h) do { _Pragma("unroll") for (int n = 0; n < 2; ++n) _Pragma("unroll") for (int k = 0; k < 2; ++k) dst[n][k] = *(const LAS bf16x8*)(lds + PG8_SB(b, h) + boff + n * 2048 + k * 1024); } while (0)
; #define PG8_MMA(ai, bj, At, Bt) do { __builtin_amdgcn_s_setprio(1); _Pragma("unroll") for (int m = 0; m < 4; ++m) _Pragma("unroll") for (int n = 0; n < 2; ++n) _Pragma("unroll") for (int k = 0; k < 2; ++k) \
;         acc[ai][bj][m][n] = __builtin_amdgcn_mfma_f32_16x16x32_bf16(Bt[n][k], At[m][k], acc[ai][bj][m][n], 0, 0, 0); __builtin_amdgcn_s_setprio(0); } while (0)
; #define PG8_WAIT_V(n) asm volatile("s_waitcnt vmcnt(" #n ")" ::: "memory")
; #define PG8_WAIT_L(n) asm volatile("s_waitcnt lgkmcnt(" #n ")" ::: "memory")
; #define PG8_BAR __builtin_amdgcn_s_barrier()
; #define PG8_SCHED __builtin_amdgcn_sched_barrier(0)
; template <class Epi, class Sched>
; DI void gemm_phase(LAS unsigned char* lds, const int K, const Sched& S, const Epi& E) {
;     ...
;             const bool last = (t == nt - 2);
;             const char* a1 = cA + (size_t)(t + 1) * kstep;
;             const char* a2 = last ? nA : cA + (size_t)(t + 2) * kstep; const char* b2 = last ? nB : cB + (size_t)(t + 2) * kstep;
;             const char* a3 = a2 + kstep; const char* b3 = b2 + kstep;
;             PG8_LDB(B0, 0, 0); PG8_LDB(B1, 0, 1); PG8_SCHED; PG8_LDA(At, 0, 0); PG8_STAGE(PG8_SA(1, 1), a1 + hstep, voffA);
;             PG8_WAIT_V(8); PG8_WAIT_L(0); PG8_BAR; PG8_MMA(0, 0, At, B0); PG8_MMA(0, 1, At, B1); PG8_BAR; PG8_SCHED;
;             PG8_LDA(At, 0, 1); PG8_STAGE(PG8_SB(0, 0), b2, voffB); PG8_STAGE(PG8_SB(0, 1), b2 + hstep, voffB); PG8_STAGE(PG8_SA(0, 0), a2, voffA);
;             PG8_WAIT_V(8); PG8_WAIT_L(0); PG8_BAR; PG8_MMA(1, 0, At, B0); PG8_MMA(1, 1, At, B1); PG8_BAR; PG8_SCHED;
.LBB0_648:
	s_add_u32 s66, s64, 0xfffc0080
	s_addc_u32 s67, s65, -1
	s_add_i32 s92, 0, 0x10000
	s_cmp_eq_u32 s63, 12
	s_cselect_b32 s69, s59, s67
	s_cselect_b32 s68, s58, s66
	v_add_u32_e32 v1, s92, v154
	s_cselect_b32 s67, s61, s57
	s_cselect_b32 s66, s60, s55
	s_add_i32 s95, 0, 0x14000
	ds_read_b128 v[142:145], v1
	s_waitcnt lgkmcnt(0)
	ds_read_b128 v[146:149], v1 offset:1024
	ds_read_b128 v[156:159], v1 offset:2048
	ds_read_b128 v[160:163], v1 offset:3072
	v_add_u32_e32 v1, s95, v154
	ds_read_b128 v[164:167], v1
	ds_read_b128 v[168:171], v1 offset:1024
	ds_read_b128 v[172:175], v1 offset:2048
	ds_read_b128 v[182:185], v1 offset:3072
	s_nop 0
	s_add_i32 m0, s76, 0xc000
	ds_read_b128 v[190:193], v155
	ds_read_b128 v[194:197], v155 offset:1024
	ds_read_b128 v[198:201], v155 offset:2048
	ds_read_b128 v[202:205], v155 offset:3072
	ds_read_b128 v[212:215], v155 offset:4096
	ds_read_b128 v[216:219], v155 offset:5120
	ds_read_b128 v[220:223], v155 offset:6144
	ds_read_b128 v[224:227], v155 offset:7168
	global_load_lds_dwordx4 v140, s[64:65]
	s_nop 0
	s_add_i32 m0, s76, 0xe000
	s_nop 0
	global_load_lds_dwordx4 v138, s[64:65]
	s_waitcnt vmcnt(8)
	s_waitcnt lgkmcnt(0)
	s_barrier
	s_nop 0
	s_waitcnt lgkmcnt(0)
	v_mfma_f32_16x16x32_bf16 v[126:129], v[142:145], v[190:193], v[126:129]
	v_mfma_f32_16x16x32_bf16 v[122:125], v[156:159], v[190:193], v[122:125]
	v_mfma_f32_16x16x32_bf16 v[110:113], v[142:145], v[198:201], v[110:113]
	v_mfma_f32_16x16x32_bf16 v[106:109], v[156:159], v[198:201], v[106:109]
	v_mfma_f32_16x16x32_bf16 v[94:97], v[142:145], v[212:215], v[94:97]
	v_mfma_f32_16x16x32_bf16 v[90:93], v[156:159], v[212:215], v[90:93]
	v_mfma_f32_16x16x32_bf16 v[78:81], v[142:145], v[220:223], v[78:81]
	v_mfma_f32_16x16x32_bf16 v[74:77], v[156:159], v[220:223], v[74:77]
	v_mfma_f32_16x16x32_bf16 v[126:129], v[146:149], v[194:197], v[126:129]
	v_mfma_f32_16x16x32_bf16 v[122:125], v[160:163], v[194:197], v[122:125]
	v_mfma_f32_16x16x32_bf16 v[110:113], v[146:149], v[202:205], v[110:113]
	v_mfma_f32_16x16x32_bf16 v[106:109], v[160:163], v[202:205], v[106:109]
	v_mfma_f32_16x16x32_bf16 v[94:97], v[146:149], v[216:219], v[94:97]
	v_mfma_f32_16x16x32_bf16 v[90:93], v[160:163], v[216:219], v[90:93]
	v_mfma_f32_16x16x32_bf16 v[78:81], v[146:149], v[224:227], v[78:81]
	v_mfma_f32_16x16x32_bf16 v[74:77], v[160:163], v[224:227], v[74:77]
	s_nop 0
	s_nop 0
	v_mfma_f32_16x16x32_bf16 v[118:121], v[164:167], v[190:193], v[118:121]
	v_mfma_f32_16x16x32_bf16 v[114:117], v[172:175], v[190:193], v[114:117]
	v_mfma_f32_16x16x32_bf16 v[102:105], v[164:167], v[198:201], v[102:105]
	v_mfma_f32_16x16x32_bf16 v[98:101], v[172:175], v[198:201], v[98:101]
	v_mfma_f32_16x16x32_bf16 v[86:89], v[164:167], v[212:215], v[86:89]
	v_mfma_f32_16x16x32_bf16 v[82:85], v[172:175], v[212:215], v[82:85]
	v_mfma_f32_16x16x32_bf16 v[70:73], v[164:167], v[220:223], v[70:73]
	v_mfma_f32_16x16x32_bf16 v[66:69], v[172:175], v[220:223], v[66:69]
	v_mfma_f32_16x16x32_bf16 v[118:121], v[168:171], v[194:197], v[118:121]
	v_mfma_f32_16x16x32_bf16 v[114:117], v[182:185], v[194:197], v[114:117]
	v_mfma_f32_16x16x32_bf16 v[102:105], v[168:171], v[202:205], v[102:105]
	v_mfma_f32_16x16x32_bf16 v[98:101], v[182:185], v[202:205], v[98:101]
	v_mfma_f32_16x16x32_bf16 v[86:89], v[168:171], v[216:219], v[86:89]
	v_mfma_f32_16x16x32_bf16 v[82:85], v[182:185], v[216:219], v[82:85]
	v_mfma_f32_16x16x32_bf16 v[70:73], v[168:171], v[224:227], v[70:73]
	v_mfma_f32_16x16x32_bf16 v[66:69], v[182:185], v[224:227], v[66:69]
	s_nop 0
	s_barrier
	s_add_i32 s92, s92, s75
	s_nop 0
	s_mov_b32 m0, s92
	ds_read_b128 v[190:193], v155 offset:16384
	ds_read_b128 v[194:197], v155 offset:17408
	ds_read_b128 v[198:201], v155 offset:18432
	ds_read_b128 v[202:205], v155 offset:19456
	ds_read_b128 v[212:215], v155 offset:20480
	ds_read_b128 v[216:219], v155 offset:21504
	ds_read_b128 v[220:223], v155 offset:22528
	ds_read_b128 v[224:227], v155 offset:23552
	global_load_lds_dwordx4 v132, s[66:67]
	s_add_i32 m0, s92, 0x2000
	s_add_u32 vcc_lo, s66, 0x40000
	s_nop 0
	s_addc_u32 vcc_hi, s67, 0
	s_add_i32 s92, s95, s75
	global_load_lds_dwordx4 v136, s[66:67]
	s_nop 0
	s_mov_b32 m0, s92
	s_nop 0
	global_load_lds_dwordx4 v132, vcc
	s_nop 0
	s_add_i32 m0, s92, 0x2000
	s_nop 0
	global_load_lds_dwordx4 v136, vcc
	s_nop 0
	s_add_u32 s98, s68, s90
	s_addc_u32 s99, s69, s91
	s_mov_b32 m0, s76
	s_nop 0
	global_load_lds_dwordx4 v130, s[68:69]
	s_mov_b32 m0, s77
	s_nop 0
	global_load_lds_dwordx4 v134, s[68:69]
	s_waitcnt vmcnt(8)
	s_waitcnt lgkmcnt(0)
	s_barrier
; #define PG8_STAGE(bufoff, gbase, voff) do { _Pragma("unroll") for (int _i = 0; _i < 2; ++_i) \
;         __builtin_amdgcn_global_load_lds((const unsigned*)((const char*)(gbase) + (voff)[_i]), (LAS unsigned*)(lds + (bufoff) + ldsw + _i * 8192), 16, 0, 0); } while (0)
; #define PG8_LDA(dst, b, h) do { _Pragma("unroll") for (int m = 0; m < 4; ++m) _Pragma("unroll") for (int k = 0; k < 2; ++k) dst[m][k] = *(const LAS bf16x8*)(lds + PG8_SA(b, h) + aoff + m * 2048 + k * 1024); } while (0)
; #define PG8_LDB(dst, b, h) do { _Pragma("unroll") for (int n = 0; n < 2; ++n) _Pragma("unroll") for (int k = 0; k < 2; ++k) dst[n][k] = *(const LAS bf16x8*)(lds + PG8_SB(b, h) + boff + n * 2048 + k * 1024); } while (0)
; #define PG8_MMA(ai, bj, At, Bt) do { __builtin_amdgcn_s_setprio(1); _Pragma("unroll") for (int m = 0; m < 4; ++m) _Pragma("unroll") for (int n = 0; n < 2; ++n) _Pragma("unroll") for (int k = 0; k < 2; ++k) \
;         acc[ai][bj][m][n] = __builtin_amdgcn_mfma_f32_16x16x32_bf16(Bt[n][k], At[m][k], acc[ai][bj][m][n], 0, 0, 0); __builtin_amdgcn_s_setprio(0); } while (0)
; #define PG8_WAIT_V(n) asm volatile("s_waitcnt vmcnt(" #n ")" ::: "memory")
; #define PG8_WAIT_L(n) asm volatile("s_waitcnt lgkmcnt(" #n ")" ::: "memory")
; #define PG8_BAR __builtin_amdgcn_s_barrier()
; #define PG8_SCHED __builtin_amdgcn_sched_barrier(0)
; template <class Epi, class Sched>
; DI void gemm_phase(LAS unsigned char* lds, const int K, const Sched& S, const Epi& E) {
;     ...
;             PG8_WAIT_V(8); PG8_WAIT_L(0); PG8_BAR; PG8_MMA(1, 0, At, B0); PG8_MMA(1, 1, At, B1); PG8_BAR; PG8_SCHED;
;             PG8_LDB(B0, 1, 0); PG8_LDB(B1, 1, 1); PG8_SCHED; PG8_LDA(At, 1, 0); PG8_STAGE(PG8_SA(0, 1), a2 + hstep, voffA);
;             PG8_WAIT_V(8); PG8_WAIT_L(0); PG8_BAR; PG8_MMA(0, 0, At, B0); PG8_MMA(0, 1, At, B1); PG8_BAR; PG8_SCHED;
	s_nop 0
	s_waitcnt lgkmcnt(0)
	v_mfma_f32_16x16x32_bf16 v[62:65], v[142:145], v[190:193], v[62:65]
	v_mfma_f32_16x16x32_bf16 v[58:61], v[156:159], v[190:193], v[58:61]
	v_mfma_f32_16x16x32_bf16 v[46:49], v[142:145], v[198:201], v[46:49]
	v_mfma_f32_16x16x32_bf16 v[42:45], v[156:159], v[198:201], v[42:45]
	v_mfma_f32_16x16x32_bf16 v[30:33], v[142:145], v[212:215], v[30:33]
	v_mfma_f32_16x16x32_bf16 v[26:29], v[156:159], v[212:215], v[26:29]
	v_mfma_f32_16x16x32_bf16 v[14:17], v[142:145], v[220:223], v[14:17]
	v_mfma_f32_16x16x32_bf16 v[10:13], v[156:159], v[220:223], v[10:13]
	v_mfma_f32_16x16x32_bf16 v[62:65], v[146:149], v[194:197], v[62:65]
	v_mfma_f32_16x16x32_bf16 v[58:61], v[160:163], v[194:197], v[58:61]
	v_mfma_f32_16x16x32_bf16 v[46:49], v[146:149], v[202:205], v[46:49]
	v_mfma_f32_16x16x32_bf16 v[42:45], v[160:163], v[202:205], v[42:45]
	v_mfma_f32_16x16x32_bf16 v[30:33], v[146:149], v[216:219], v[30:33]
	v_mfma_f32_16x16x32_bf16 v[26:29], v[160:163], v[216:219], v[26:29]
	v_mfma_f32_16x16x32_bf16 v[14:17], v[146:149], v[224:227], v[14:17]
	v_mfma_f32_16x16x32_bf16 v[10:13], v[160:163], v[224:227], v[10:13]
	s_nop 0
	s_nop 0
	v_mfma_f32_16x16x32_bf16 v[54:57], v[164:167], v[190:193], v[54:57]
	v_mfma_f32_16x16x32_bf16 v[50:53], v[172:175], v[190:193], v[50:53]
	v_mfma_f32_16x16x32_bf16 v[38:41], v[164:167], v[198:201], v[38:41]
	v_mfma_f32_16x16x32_bf16 v[34:37], v[172:175], v[198:201], v[34:37]
	v_mfma_f32_16x16x32_bf16 v[22:25], v[164:167], v[212:215], v[22:25]
	v_mfma_f32_16x16x32_bf16 v[18:21], v[172:175], v[212:215], v[18:21]
	v_mfma_f32_16x16x32_bf16 v[6:9], v[164:167], v[220:223], v[6:9]
	v_mfma_f32_16x16x32_bf16 v[2:5], v[172:175], v[220:223], v[2:5]
	v_mfma_f32_16x16x32_bf16 v[54:57], v[168:171], v[194:197], v[54:57]
	v_mfma_f32_16x16x32_bf16 v[50:53], v[182:185], v[194:197], v[50:53]
	v_mfma_f32_16x16x32_bf16 v[38:41], v[168:171], v[202:205], v[38:41]
	v_mfma_f32_16x16x32_bf16 v[34:37], v[182:185], v[202:205], v[34:37]
	v_mfma_f32_16x16x32_bf16 v[22:25], v[168:171], v[216:219], v[22:25]
	v_mfma_f32_16x16x32_bf16 v[18:21], v[182:185], v[216:219], v[18:21]
	v_mfma_f32_16x16x32_bf16 v[6:9], v[168:171], v[224:227], v[6:9]
	v_mfma_f32_16x16x32_bf16 v[2:5], v[182:185], v[224:227], v[2:5]
	s_nop 0
	s_barrier
	s_add_i32 s92, 0, 0x18000
	v_add_u32_e32 v1, s92, v154
	s_add_i32 s95, 0, 0x1c000
	ds_read_b128 v[142:145], v1
	ds_read_b128 v[146:149], v1 offset:1024
	ds_read_b128 v[156:159], v1 offset:2048
	ds_read_b128 v[160:163], v1 offset:3072
	v_add_u32_e32 v1, s95, v154
	ds_read_b128 v[164:167], v1
	ds_read_b128 v[168:171], v1 offset:1024
	ds_read_b128 v[172:175], v1 offset:2048
	ds_read_b128 v[182:185], v1 offset:3072
	s_add_u32 s68, s68, 0x40000
	s_addc_u32 s69, s69, 0
	s_mov_b32 m0, s78
	s_nop 0
	ds_read_b128 v[190:193], v155 offset:32768
	ds_read_b128 v[194:197], v155 offset:33792
	ds_read_b128 v[198:201], v155 offset:34816
	ds_read_b128 v[202:205], v155 offset:35840
	ds_read_b128 v[212:215], v155 offset:36864
	ds_read_b128 v[216:219], v155 offset:37888
	ds_read_b128 v[220:223], v155 offset:38912
	ds_read_b128 v[224:227], v155 offset:39936
	global_load_lds_dwordx4 v130, s[68:69]
	s_nop 0
	s_mov_b32 m0, s79
	s_nop 0
	global_load_lds_dwordx4 v134, s[68:69]
	s_waitcnt vmcnt(8)
	s_waitcnt lgkmcnt(0)
	s_barrier
	s_nop 0
	s_waitcnt lgkmcnt(0)
	v_mfma_f32_16x16x32_bf16 v[126:129], v[142:145], v[190:193], v[126:129]
	v_mfma_f32_16x16x32_bf16 v[122:125], v[156:159], v[190:193], v[122:125]
	v_mfma_f32_16x16x32_bf16 v[110:113], v[142:145], v[198:201], v[110:113]
	v_mfma_f32_16x16x32_bf16 v[106:109], v[156:159], v[198:201], v[106:109]
	v_mfma_f32_16x16x32_bf16 v[94:97], v[142:145], v[212:215], v[94:97]
	v_mfma_f32_16x16x32_bf16 v[90:93], v[156:159], v[212:215], v[90:93]
	v_mfma_f32_16x16x32_bf16 v[78:81], v[142:145], v[220:223], v[78:81]
	v_mfma_f32_16x16x32_bf16 v[74:77], v[156:159], v[220:223], v[74:77]
	v_mfma_f32_16x16x32_bf16 v[126:129], v[146:149], v[194:197], v[126:129]
	v_mfma_f32_16x16x32_bf16 v[122:125], v[160:163], v[194:197], v[122:125]
	v_mfma_f32_16x16x32_bf16 v[110:113], v[146:149], v[202:205], v[110:113]
	v_mfma_f32_16x16x32_bf16 v[106:109], v[160:163], v[202:205], v[106:109]
	v_mfma_f32_16x16x32_bf16 v[94:97], v[146:149], v[216:219], v[94:97]
	v_mfma_f32_16x16x32_bf16 v[90:93], v[160:163], v[216:219], v[90:93]
	v_mfma_f32_16x16x32_bf16 v[78:81], v[146:149], v[224:227], v[78:81]
	v_mfma_f32_16x16x32_bf16 v[74:77], v[160:163], v[224:227], v[74:77]
	s_nop 0
	s_nop 0
	v_mfma_f32_16x16x32_bf16 v[118:121], v[164:167], v[190:193], v[118:121]
	v_mfma_f32_16x16x32_bf16 v[114:117], v[172:175], v[190:193], v[114:117]
	v_mfma_f32_16x16x32_bf16 v[102:105], v[164:167], v[198:201], v[102:105]
	v_mfma_f32_16x16x32_bf16 v[98:101], v[172:175], v[198:201], v[98:101]
	v_mfma_f32_16x16x32_bf16 v[86:89], v[164:167], v[212:215], v[86:89]
	v_mfma_f32_16x16x32_bf16 v[82:85], v[172:175], v[212:215], v[82:85]
	v_mfma_f32_16x16x32_bf16 v[70:73], v[164:167], v[220:223], v[70:73]
	v_mfma_f32_16x16x32_bf16 v[66:69], v[172:175], v[220:223], v[66:69]
	v_mfma_f32_16x16x32_bf16 v[118:121], v[168:171], v[194:197], v[118:121]
	v_mfma_f32_16x16x32_bf16 v[114:117], v[182:185], v[194:197], v[114:117]
	v_mfma_f32_16x16x32_bf16 v[102:105], v[168:171], v[202:205], v[102:105]
	v_mfma_f32_16x16x32_bf16 v[98:101], v[182:185], v[202:205], v[98:101]
	v_mfma_f32_16x16x32_bf16 v[86:89], v[168:171], v[216:219], v[86:89]
	v_mfma_f32_16x16x32_bf16 v[82:85], v[182:185], v[216:219], v[82:85]
	v_mfma_f32_16x16x32_bf16 v[70:73], v[168:171], v[224:227], v[70:73]
	v_mfma_f32_16x16x32_bf16 v[66:69], v[182:185], v[224:227], v[66:69]
	s_nop 0
	s_barrier
; #define PG8_STAGE(bufoff, gbase, voff) do { _Pragma("unroll") for (int _i = 0; _i < 2; ++_i) \
;         __builtin_amdgcn_global_load_lds((const unsigned*)((const char*)(gbase) + (voff)[_i]), (LAS unsigned*)(lds + (bufoff) + ldsw + _i * 8192), 16, 0, 0); } while (0)
; #define PG8_LDA(dst, b, h) do { _Pragma("unroll") for (int m = 0; m < 4; ++m) _Pragma("unroll") for (int k = 0; k < 2; ++k) dst[m][k] = *(const LAS bf16x8*)(lds + PG8_SA(b, h) + aoff + m * 2048 + k * 1024); } while (0)
; #define PG8_MMA(ai, bj, At, Bt) do { __builtin_amdgcn_s_setprio(1); _Pragma("unroll") for (int m = 0; m < 4; ++m) _Pragma("unroll") for (int n = 0; n < 2; ++n) _Pragma("unroll") for (int k = 0; k < 2; ++k) \
;         acc[ai][bj][m][n] = __builtin_amdgcn_mfma_f32_16x16x32_bf16(Bt[n][k], At[m][k], acc[ai][bj][m][n], 0, 0, 0); __builtin_amdgcn_s_setprio(0); } while (0)
; #define PG8_WAIT_V(n) asm volatile("s_waitcnt vmcnt(" #n ")" ::: "memory")
; #define PG8_WAIT_L(n) asm volatile("s_waitcnt lgkmcnt(" #n ")" ::: "memory")
; #define PG8_BAR __builtin_amdgcn_s_barrier()
; #define PG8_SCHED __builtin_amdgcn_sched_barrier(0)
; template <class Epi, class Sched>
; DI void gemm_phase(LAS unsigned char* lds, const int K, const Sched& S, const Epi& E) {
;     ...
;             PG8_LDA(At, 1, 1); PG8_STAGE(PG8_SB(1, 0), b3, voffB); PG8_STAGE(PG8_SB(1, 1), b3 + hstep, voffB); PG8_STAGE(PG8_SA(1, 0), a3, voffA);
;             PG8_WAIT_V(8); PG8_WAIT_L(0); PG8_BAR; PG8_MMA(1, 0, At, B0); PG8_MMA(1, 1, At, B1); PG8_BAR; PG8_SCHED;
;         }
;         if (wr == 0) PG8_BAR;
	s_add_i32 s68, s92, s75
	s_add_u32 s66, s66, 0x80
	s_addc_u32 s67, s67, 0
	s_mov_b32 m0, s68
	ds_read_b128 v[190:193], v155 offset:49152
	ds_read_b128 v[194:197], v155 offset:50176
	ds_read_b128 v[198:201], v155 offset:51200
	ds_read_b128 v[202:205], v155 offset:52224
	ds_read_b128 v[212:215], v155 offset:53248
	ds_read_b128 v[216:219], v155 offset:54272
	ds_read_b128 v[220:223], v155 offset:55296
	ds_read_b128 v[224:227], v155 offset:56320
	global_load_lds_dwordx4 v132, s[66:67]
	s_add_i32 m0, s68, 0x2000
	s_nop 0
	s_nop 0
	s_nop 0
	s_add_i32 s68, s95, s75
	global_load_lds_dwordx4 v136, s[66:67]
	s_add_u32 s66, s66, 0x40000
	s_addc_u32 s67, s67, 0
	s_nop 0
	s_mov_b32 m0, s68
	s_nop 0
	global_load_lds_dwordx4 v132, s[66:67]
	s_nop 0
	s_add_i32 m0, s68, 0x2000
	s_nop 0
	global_load_lds_dwordx4 v136, s[66:67]
	s_nop 0
	s_mov_b32 m0, s83
	s_nop 0
	global_load_lds_dwordx4 v130, s[98:99]
	s_nop 0
	s_mov_b32 m0, s84
	s_nop 0
	global_load_lds_dwordx4 v134, s[98:99]
	s_waitcnt vmcnt(8)
	s_waitcnt lgkmcnt(0)
	s_barrier
	s_nop 0
	s_waitcnt lgkmcnt(0)
	v_mfma_f32_16x16x32_bf16 v[62:65], v[142:145], v[190:193], v[62:65]
	v_mfma_f32_16x16x32_bf16 v[58:61], v[156:159], v[190:193], v[58:61]
	v_mfma_f32_16x16x32_bf16 v[46:49], v[142:145], v[198:201], v[46:49]
	v_mfma_f32_16x16x32_bf16 v[42:45], v[156:159], v[198:201], v[42:45]
	v_mfma_f32_16x16x32_bf16 v[30:33], v[142:145], v[212:215], v[30:33]
	v_mfma_f32_16x16x32_bf16 v[26:29], v[156:159], v[212:215], v[26:29]
	v_mfma_f32_16x16x32_bf16 v[14:17], v[142:145], v[220:223], v[14:17]
	v_mfma_f32_16x16x32_bf16 v[10:13], v[156:159], v[220:223], v[10:13]
	v_mfma_f32_16x16x32_bf16 v[62:65], v[146:149], v[194:197], v[62:65]
	v_mfma_f32_16x16x32_bf16 v[58:61], v[160:163], v[194:197], v[58:61]
	v_mfma_f32_16x16x32_bf16 v[46:49], v[146:149], v[202:205], v[46:49]
	v_mfma_f32_16x16x32_bf16 v[42:45], v[160:163], v[202:205], v[42:45]
	v_mfma_f32_16x16x32_bf16 v[30:33], v[146:149], v[216:219], v[30:33]
	v_mfma_f32_16x16x32_bf16 v[26:29], v[160:163], v[216:219], v[26:29]
	v_mfma_f32_16x16x32_bf16 v[14:17], v[146:149], v[224:227], v[14:17]
	v_mfma_f32_16x16x32_bf16 v[10:13], v[160:163], v[224:227], v[10:13]
	s_nop 0
	s_nop 0
	v_mfma_f32_16x16x32_bf16 v[54:57], v[164:167], v[190:193], v[54:57]
	v_mfma_f32_16x16x32_bf16 v[50:53], v[172:175], v[190:193], v[50:53]
	v_mfma_f32_16x16x32_bf16 v[38:41], v[164:167], v[198:201], v[38:41]
	v_mfma_f32_16x16x32_bf16 v[34:37], v[172:175], v[198:201], v[34:37]
	v_mfma_f32_16x16x32_bf16 v[22:25], v[164:167], v[212:215], v[22:25]
	v_mfma_f32_16x16x32_bf16 v[18:21], v[172:175], v[212:215], v[18:21]
	v_mfma_f32_16x16x32_bf16 v[6:9], v[164:167], v[220:223], v[6:9]
	v_mfma_f32_16x16x32_bf16 v[2:5], v[172:175], v[220:223], v[2:5]
	v_mfma_f32_16x16x32_bf16 v[54:57], v[168:171], v[194:197], v[54:57]
	v_mfma_f32_16x16x32_bf16 v[50:53], v[182:185], v[194:197], v[50:53]
	v_mfma_f32_16x16x32_bf16 v[38:41], v[168:171], v[202:205], v[38:41]
	v_mfma_f32_16x16x32_bf16 v[34:37], v[182:185], v[202:205], v[34:37]
	v_mfma_f32_16x16x32_bf16 v[22:25], v[168:171], v[216:219], v[22:25]
	v_mfma_f32_16x16x32_bf16 v[18:21], v[182:185], v[216:219], v[18:21]
	v_mfma_f32_16x16x32_bf16 v[6:9], v[168:171], v[224:227], v[6:9]
	v_mfma_f32_16x16x32_bf16 v[2:5], v[182:185], v[224:227], v[2:5]
	s_nop 0
	s_barrier
	s_add_i32 s63, s63, 2
	s_add_u32 s55, s55, 0x100
	s_addc_u32 s57, s57, 0
	s_add_u32 s64, s64, 0x100
	s_addc_u32 s65, s65, 0
	s_cmp_gt_u32 s63, 13
	s_cbranch_scc0 .LBB0_648
	s_and_b64 vcc, exec, s[46:47]
	s_cbranch_vccz .LBB0_651
	s_barrier

; #define PG8_STAGE(bufoff, gbase, voff) do { _Pragma("unroll") for (int _i = 0; _i < 2; ++_i) \
;         __builtin_amdgcn_global_load_lds((const unsigned*)((const char*)(gbase) + (voff)[_i]), (LAS unsigned*)(lds + (bufoff) + ldsw + _i * 8192), 16, 0, 0); } while (0)
; #define PG8_LDA(dst, b, h) do { _Pragma("unroll") for (int m = 0; m < 4; ++m) _Pragma("unroll") for (int k = 0; k < 2; ++k) dst[m][k] = *(const LAS bf16x8*)(lds + PG8_SA(b, h) + aoff + m * 2048 + k * 1024); } while (0)
; #define PG8_LDB(dst, b, h) do { _Pragma("unroll") for (int n = 0; n < 2; ++n) _Pragma("unroll") for (int k = 0; k < 2; ++k) dst[n][k] = *(const LAS bf16x8*)(lds + PG8_SB(b, h) + boff + n * 2048 + k * 1024); } while (0)
; #define PG8_MMA(ai, bj, At, Bt) do { __builtin_amdgcn_s_setprio(1); _Pragma("unroll") for (int m = 0; m < 4; ++m) _Pragma("unroll") for (int n = 0; n < 2; ++n) _Pragma("unroll") for (int k = 0; k < 2; ++k) \
;         acc[ai][bj][m][n] = __builtin_amdgcn_mfma_f32_16x16x32_bf16(Bt[n][k], At[m][k], acc[ai][bj][m][n], 0, 0, 0); __builtin_amdgcn_s_setprio(0); } while (0)
; #define PG8_WAIT_V(n) asm volatile("s_waitcnt vmcnt(" #n ")" ::: "memory")
; #define PG8_WAIT_L(n) asm volatile("s_waitcnt lgkmcnt(" #n ")" ::: "memory")
; #define PG8_BAR __builtin_amdgcn_s_barrier()
; #define PG8_SCHED __builtin_amdgcn_sched_barrier(0)
; template <class Epi, class Sched>
; DI void gemm_phase(LAS unsigned char* lds, const int K, const Sched& S, const Epi& E) {
;     ...
;             const bool last = (t == nt - 2);
;             const char* a1 = cA + (size_t)(t + 1) * kstep;
;             const char* a2 = last ? nA : cA + (size_t)(t + 2) * kstep; const char* b2 = last ? nB : cB + (size_t)(t + 2) * kstep;
;             const char* a3 = a2 + kstep; const char* b3 = b2 + kstep;
;             PG8_LDB(B0, 0, 0); PG8_LDB(B1, 0, 1); PG8_SCHED; PG8_LDA(At, 0, 0); PG8_STAGE(PG8_SA(1, 1), a1 + hstep, voffA);
;             PG8_WAIT_V(8); PG8_WAIT_L(0); PG8_BAR; PG8_MMA(0, 0, At, B0); PG8_MMA(0, 1, At, B1); PG8_BAR; PG8_SCHED;
;             PG8_LDA(At, 0, 1); PG8_STAGE(PG8_SB(0, 0), b2, voffB); PG8_STAGE(PG8_SB(0, 1), b2 + hstep, voffB); PG8_STAGE(PG8_SA(0, 0), a2, voffA);
;             PG8_WAIT_V(8); PG8_WAIT_L(0); PG8_BAR; PG8_MMA(1, 0, At, B0); PG8_MMA(1, 1, At, B1); PG8_BAR; PG8_SCHED;
.LBB0_784:
	s_add_u32 s48, s44, 0xfffc0080
	s_addc_u32 s49, s45, -1
	s_add_i32 s77, 0, 0x10000
	s_cmp_eq_u32 s76, 12
	s_cselect_b32 s75, s69, s49
	s_cselect_b32 s74, s68, s48
	s_cselect_b32 s73, s71, s67
	s_cselect_b32 s72, s70, s65
	s_add_i32 s48, 0, 0x14000
	v_add_u32_e32 v142, s77, v199
	v_add_u32_e32 v158, s48, v199
	ds_read_b128 v[130:133], v142
	ds_read_b128 v[134:137], v142 offset:1024
	ds_read_b128 v[138:141], v142 offset:2048
	ds_read_b128 v[142:145], v142 offset:3072
	ds_read_b128 v[146:149], v158
	ds_read_b128 v[150:153], v158 offset:1024
	ds_read_b128 v[154:157], v158 offset:2048
	ds_read_b128 v[158:161], v158 offset:3072
	s_nop 0
	s_add_i32 m0, s80, 0xc000
	ds_read_b128 v[174:177], v200
	ds_read_b128 v[182:185], v200 offset:1024
	ds_read_b128 v[190:193], v200 offset:2048
	ds_read_b128 v[194:197], v200 offset:3072
	ds_read_b128 v[202:205], v200 offset:4096
	ds_read_b128 v[212:215], v200 offset:5120
	ds_read_b128 v[216:219], v200 offset:6144
	ds_read_b128 v[220:223], v200 offset:7168
	global_load_lds_dwordx4 v172, s[44:45]
	s_nop 0
	s_add_i32 m0, s80, 0xe000
	s_nop 0
	global_load_lds_dwordx4 v170, s[44:45]
	s_waitcnt vmcnt(8)
	s_waitcnt lgkmcnt(0)
	s_barrier
	s_nop 0
	s_waitcnt lgkmcnt(0)
	v_mfma_f32_16x16x32_bf16 v[126:129], v[130:133], v[174:177], v[126:129]
	v_mfma_f32_16x16x32_bf16 v[122:125], v[138:141], v[174:177], v[122:125]
	v_mfma_f32_16x16x32_bf16 v[118:121], v[130:133], v[190:193], v[118:121]
	v_mfma_f32_16x16x32_bf16 v[114:117], v[138:141], v[190:193], v[114:117]
	v_mfma_f32_16x16x32_bf16 v[110:113], v[130:133], v[202:205], v[110:113]
	v_mfma_f32_16x16x32_bf16 v[106:109], v[138:141], v[202:205], v[106:109]
	v_mfma_f32_16x16x32_bf16 v[102:105], v[130:133], v[216:219], v[102:105]
	v_mfma_f32_16x16x32_bf16 v[98:101], v[138:141], v[216:219], v[98:101]
	v_mfma_f32_16x16x32_bf16 v[126:129], v[134:137], v[182:185], v[126:129]
	v_mfma_f32_16x16x32_bf16 v[122:125], v[142:145], v[182:185], v[122:125]
	v_mfma_f32_16x16x32_bf16 v[118:121], v[134:137], v[194:197], v[118:121]
	v_mfma_f32_16x16x32_bf16 v[114:117], v[142:145], v[194:197], v[114:117]
	v_mfma_f32_16x16x32_bf16 v[110:113], v[134:137], v[212:215], v[110:113]
	v_mfma_f32_16x16x32_bf16 v[106:109], v[142:145], v[212:215], v[106:109]
	v_mfma_f32_16x16x32_bf16 v[102:105], v[134:137], v[220:223], v[102:105]
	v_mfma_f32_16x16x32_bf16 v[98:101], v[142:145], v[220:223], v[98:101]
	s_nop 0
	s_nop 0
	v_mfma_f32_16x16x32_bf16 v[94:97], v[146:149], v[174:177], v[94:97]
	v_mfma_f32_16x16x32_bf16 v[90:93], v[154:157], v[174:177], v[90:93]
	v_mfma_f32_16x16x32_bf16 v[86:89], v[146:149], v[190:193], v[86:89]
	v_mfma_f32_16x16x32_bf16 v[82:85], v[154:157], v[190:193], v[82:85]
	v_mfma_f32_16x16x32_bf16 v[78:81], v[146:149], v[202:205], v[78:81]
	v_mfma_f32_16x16x32_bf16 v[74:77], v[154:157], v[202:205], v[74:77]
	v_mfma_f32_16x16x32_bf16 v[70:73], v[146:149], v[216:219], v[70:73]
	v_mfma_f32_16x16x32_bf16 v[66:69], v[154:157], v[216:219], v[66:69]
	v_mfma_f32_16x16x32_bf16 v[94:97], v[150:153], v[182:185], v[94:97]
	v_mfma_f32_16x16x32_bf16 v[90:93], v[158:161], v[182:185], v[90:93]
	v_mfma_f32_16x16x32_bf16 v[86:89], v[150:153], v[194:197], v[86:89]
	v_mfma_f32_16x16x32_bf16 v[82:85], v[158:161], v[194:197], v[82:85]
	v_mfma_f32_16x16x32_bf16 v[78:81], v[150:153], v[212:215], v[78:81]
	v_mfma_f32_16x16x32_bf16 v[74:77], v[158:161], v[212:215], v[74:77]
	v_mfma_f32_16x16x32_bf16 v[70:73], v[150:153], v[220:223], v[70:73]
	v_mfma_f32_16x16x32_bf16 v[66:69], v[158:161], v[220:223], v[66:69]
	s_nop 0
	s_barrier
	s_add_i32 s49, s77, s79
	s_nop 0
	s_mov_b32 m0, s49
	ds_read_b128 v[174:177], v200 offset:16384
	ds_read_b128 v[182:185], v200 offset:17408
	ds_read_b128 v[190:193], v200 offset:18432
	ds_read_b128 v[194:197], v200 offset:19456
	ds_read_b128 v[202:205], v200 offset:20480
	ds_read_b128 v[212:215], v200 offset:21504
	ds_read_b128 v[216:219], v200 offset:22528
	ds_read_b128 v[220:223], v200 offset:23552
	global_load_lds_dwordx4 v164, s[72:73]
	s_add_i32 m0, s49, 0x2000
	s_add_u32 vcc_lo, s72, 0x40000
	s_nop 0
	s_addc_u32 vcc_hi, s73, 0
	s_add_i32 s48, s48, s79
	global_load_lds_dwordx4 v168, s[72:73]
	s_nop 0
	s_mov_b32 m0, s48
	s_nop 0
	global_load_lds_dwordx4 v164, vcc
	s_nop 0
	s_add_i32 m0, s48, 0x2000
	s_nop 0
	global_load_lds_dwordx4 v168, vcc
	s_nop 0
	s_add_u32 s98, s74, s90
	s_addc_u32 s99, s75, s91
	s_mov_b32 m0, s80
	s_nop 0
	global_load_lds_dwordx4 v162, s[74:75]
	s_mov_b32 m0, s81
	s_nop 0
	global_load_lds_dwordx4 v166, s[74:75]
	s_waitcnt vmcnt(8)
	s_waitcnt lgkmcnt(0)
	s_barrier
; #define PG8_STAGE(bufoff, gbase, voff) do { _Pragma("unroll") for (int _i = 0; _i < 2; ++_i) \
;         __builtin_amdgcn_global_load_lds((const unsigned*)((const char*)(gbase) + (voff)[_i]), (LAS unsigned*)(lds + (bufoff) + ldsw + _i * 8192), 16, 0, 0); } while (0)
; #define PG8_LDA(dst, b, h) do { _Pragma("unroll") for (int m = 0; m < 4; ++m) _Pragma("unroll") for (int k = 0; k < 2; ++k) dst[m][k] = *(const LAS bf16x8*)(lds + PG8_SA(b, h) + aoff + m * 2048 + k * 1024); } while (0)
; #define PG8_LDB(dst, b, h) do { _Pragma("unroll") for (int n = 0; n < 2; ++n) _Pragma("unroll") for (int k = 0; k < 2; ++k) dst[n][k] = *(const LAS bf16x8*)(lds + PG8_SB(b, h) + boff + n * 2048 + k * 1024); } while (0)
; #define PG8_MMA(ai, bj, At, Bt) do { __builtin_amdgcn_s_setprio(1); _Pragma("unroll") for (int m = 0; m < 4; ++m) _Pragma("unroll") for (int n = 0; n < 2; ++n) _Pragma("unroll") for (int k = 0; k < 2; ++k) \
;         acc[ai][bj][m][n] = __builtin_amdgcn_mfma_f32_16x16x32_bf16(Bt[n][k], At[m][k], acc[ai][bj][m][n], 0, 0, 0); __builtin_amdgcn_s_setprio(0); } while (0)
; #define PG8_WAIT_V(n) asm volatile("s_waitcnt vmcnt(" #n ")" ::: "memory")
; #define PG8_WAIT_L(n) asm volatile("s_waitcnt lgkmcnt(" #n ")" ::: "memory")
; #define PG8_BAR __builtin_amdgcn_s_barrier()
; #define PG8_SCHED __builtin_amdgcn_sched_barrier(0)
; template <class Epi, class Sched>
; DI void gemm_phase(LAS unsigned char* lds, const int K, const Sched& S, const Epi& E) {
;     ...
;             PG8_WAIT_V(8); PG8_WAIT_L(0); PG8_BAR; PG8_MMA(1, 0, At, B0); PG8_MMA(1, 1, At, B1); PG8_BAR; PG8_SCHED;
;             PG8_LDB(B0, 1, 0); PG8_LDB(B1, 1, 1); PG8_SCHED; PG8_LDA(At, 1, 0); PG8_STAGE(PG8_SA(0, 1), a2 + hstep, voffA);
;             PG8_WAIT_V(8); PG8_WAIT_L(0); PG8_BAR; PG8_MMA(0, 0, At, B0); PG8_MMA(0, 1, At, B1); PG8_BAR; PG8_SCHED;
	s_nop 0
	s_waitcnt lgkmcnt(0)
	v_mfma_f32_16x16x32_bf16 v[62:65], v[130:133], v[174:177], v[62:65]
	v_mfma_f32_16x16x32_bf16 v[58:61], v[138:141], v[174:177], v[58:61]
	v_mfma_f32_16x16x32_bf16 v[54:57], v[130:133], v[190:193], v[54:57]
	v_mfma_f32_16x16x32_bf16 v[50:53], v[138:141], v[190:193], v[50:53]
	v_mfma_f32_16x16x32_bf16 v[46:49], v[130:133], v[202:205], v[46:49]
	v_mfma_f32_16x16x32_bf16 v[42:45], v[138:141], v[202:205], v[42:45]
	v_mfma_f32_16x16x32_bf16 v[38:41], v[130:133], v[216:219], v[38:41]
	v_mfma_f32_16x16x32_bf16 v[34:37], v[138:141], v[216:219], v[34:37]
	v_mfma_f32_16x16x32_bf16 v[62:65], v[134:137], v[182:185], v[62:65]
	v_mfma_f32_16x16x32_bf16 v[58:61], v[142:145], v[182:185], v[58:61]
	v_mfma_f32_16x16x32_bf16 v[54:57], v[134:137], v[194:197], v[54:57]
	v_mfma_f32_16x16x32_bf16 v[50:53], v[142:145], v[194:197], v[50:53]
	v_mfma_f32_16x16x32_bf16 v[46:49], v[134:137], v[212:215], v[46:49]
	v_mfma_f32_16x16x32_bf16 v[42:45], v[142:145], v[212:215], v[42:45]
	v_mfma_f32_16x16x32_bf16 v[38:41], v[134:137], v[220:223], v[38:41]
	v_mfma_f32_16x16x32_bf16 v[34:37], v[142:145], v[220:223], v[34:37]
	s_nop 0
	s_nop 0
	v_mfma_f32_16x16x32_bf16 v[30:33], v[146:149], v[174:177], v[30:33]
	v_mfma_f32_16x16x32_bf16 v[26:29], v[154:157], v[174:177], v[26:29]
	v_mfma_f32_16x16x32_bf16 v[22:25], v[146:149], v[190:193], v[22:25]
	v_mfma_f32_16x16x32_bf16 v[18:21], v[154:157], v[190:193], v[18:21]
	v_mfma_f32_16x16x32_bf16 v[14:17], v[146:149], v[202:205], v[14:17]
	v_mfma_f32_16x16x32_bf16 v[10:13], v[154:157], v[202:205], v[10:13]
	v_mfma_f32_16x16x32_bf16 v[6:9], v[146:149], v[216:219], v[6:9]
	v_mfma_f32_16x16x32_bf16 v[2:5], v[154:157], v[216:219], v[2:5]
	v_mfma_f32_16x16x32_bf16 v[30:33], v[150:153], v[182:185], v[30:33]
	v_mfma_f32_16x16x32_bf16 v[26:29], v[158:161], v[182:185], v[26:29]
	v_mfma_f32_16x16x32_bf16 v[22:25], v[150:153], v[194:197], v[22:25]
	v_mfma_f32_16x16x32_bf16 v[18:21], v[158:161], v[194:197], v[18:21]
	v_mfma_f32_16x16x32_bf16 v[14:17], v[150:153], v[212:215], v[14:17]
	v_mfma_f32_16x16x32_bf16 v[10:13], v[158:161], v[212:215], v[10:13]
	v_mfma_f32_16x16x32_bf16 v[6:9], v[150:153], v[220:223], v[6:9]
	v_mfma_f32_16x16x32_bf16 v[2:5], v[158:161], v[220:223], v[2:5]
	s_nop 0
	s_barrier
	s_add_i32 s48, 0, 0x18000
	s_add_i32 s49, 0, 0x1c000
	v_add_u32_e32 v142, s48, v199
	v_add_u32_e32 v158, s49, v199
	ds_read_b128 v[130:133], v142
	ds_read_b128 v[134:137], v142 offset:1024
	ds_read_b128 v[138:141], v142 offset:2048
	ds_read_b128 v[142:145], v142 offset:3072
	ds_read_b128 v[146:149], v158
	ds_read_b128 v[150:153], v158 offset:1024
	ds_read_b128 v[154:157], v158 offset:2048
	ds_read_b128 v[158:161], v158 offset:3072
	s_add_u32 s74, s74, 0x40000
	s_addc_u32 s75, s75, 0
	s_mov_b32 m0, s85
	s_nop 0
	ds_read_b128 v[174:177], v200 offset:32768
	ds_read_b128 v[182:185], v200 offset:33792
	ds_read_b128 v[190:193], v200 offset:34816
	ds_read_b128 v[194:197], v200 offset:35840
	ds_read_b128 v[202:205], v200 offset:36864
	ds_read_b128 v[212:215], v200 offset:37888
	ds_read_b128 v[216:219], v200 offset:38912
	ds_read_b128 v[220:223], v200 offset:39936
	global_load_lds_dwordx4 v162, s[74:75]
	s_nop 0
	s_mov_b32 m0, s86
	s_nop 0
	global_load_lds_dwordx4 v166, s[74:75]
	s_waitcnt vmcnt(8)
	s_waitcnt lgkmcnt(0)
	s_barrier
	s_nop 0
	s_waitcnt lgkmcnt(0)
	v_mfma_f32_16x16x32_bf16 v[126:129], v[130:133], v[174:177], v[126:129]
	v_mfma_f32_16x16x32_bf16 v[122:125], v[138:141], v[174:177], v[122:125]
	v_mfma_f32_16x16x32_bf16 v[118:121], v[130:133], v[190:193], v[118:121]
	v_mfma_f32_16x16x32_bf16 v[114:117], v[138:141], v[190:193], v[114:117]
	v_mfma_f32_16x16x32_bf16 v[110:113], v[130:133], v[202:205], v[110:113]
	v_mfma_f32_16x16x32_bf16 v[106:109], v[138:141], v[202:205], v[106:109]
	v_mfma_f32_16x16x32_bf16 v[102:105], v[130:133], v[216:219], v[102:105]
	v_mfma_f32_16x16x32_bf16 v[98:101], v[138:141], v[216:219], v[98:101]
	v_mfma_f32_16x16x32_bf16 v[126:129], v[134:137], v[182:185], v[126:129]
	v_mfma_f32_16x16x32_bf16 v[122:125], v[142:145], v[182:185], v[122:125]
	v_mfma_f32_16x16x32_bf16 v[118:121], v[134:137], v[194:197], v[118:121]
	v_mfma_f32_16x16x32_bf16 v[114:117], v[142:145], v[194:197], v[114:117]
	v_mfma_f32_16x16x32_bf16 v[110:113], v[134:137], v[212:215], v[110:113]
	v_mfma_f32_16x16x32_bf16 v[106:109], v[142:145], v[212:215], v[106:109]
	v_mfma_f32_16x16x32_bf16 v[102:105], v[134:137], v[220:223], v[102:105]
	v_mfma_f32_16x16x32_bf16 v[98:101], v[142:145], v[220:223], v[98:101]
	s_nop 0
	s_nop 0
	v_mfma_f32_16x16x32_bf16 v[94:97], v[146:149], v[174:177], v[94:97]
	v_mfma_f32_16x16x32_bf16 v[90:93], v[154:157], v[174:177], v[90:93]
	v_mfma_f32_16x16x32_bf16 v[86:89], v[146:149], v[190:193], v[86:89]
	v_mfma_f32_16x16x32_bf16 v[82:85], v[154:157], v[190:193], v[82:85]
	v_mfma_f32_16x16x32_bf16 v[78:81], v[146:149], v[202:205], v[78:81]
	v_mfma_f32_16x16x32_bf16 v[74:77], v[154:157], v[202:205], v[74:77]
	v_mfma_f32_16x16x32_bf16 v[70:73], v[146:149], v[216:219], v[70:73]
	v_mfma_f32_16x16x32_bf16 v[66:69], v[154:157], v[216:219], v[66:69]
	v_mfma_f32_16x16x32_bf16 v[94:97], v[150:153], v[182:185], v[94:97]
	v_mfma_f32_16x16x32_bf16 v[90:93], v[158:161], v[182:185], v[90:93]
	v_mfma_f32_16x16x32_bf16 v[86:89], v[150:153], v[194:197], v[86:89]
	v_mfma_f32_16x16x32_bf16 v[82:85], v[158:161], v[194:197], v[82:85]
	v_mfma_f32_16x16x32_bf16 v[78:81], v[150:153], v[212:215], v[78:81]
	v_mfma_f32_16x16x32_bf16 v[74:77], v[158:161], v[212:215], v[74:77]
	v_mfma_f32_16x16x32_bf16 v[70:73], v[150:153], v[220:223], v[70:73]
	v_mfma_f32_16x16x32_bf16 v[66:69], v[158:161], v[220:223], v[66:69]
	s_nop 0
	s_barrier
; #define PG8_STAGE(bufoff, gbase, voff) do { _Pragma("unroll") for (int _i = 0; _i < 2; ++_i) \
;         __builtin_amdgcn_global_load_lds((const unsigned*)((const char*)(gbase) + (voff)[_i]), (LAS unsigned*)(lds + (bufoff) + ldsw + _i * 8192), 16, 0, 0); } while (0)
; #define PG8_LDA(dst, b, h) do { _Pragma("unroll") for (int m = 0; m < 4; ++m) _Pragma("unroll") for (int k = 0; k < 2; ++k) dst[m][k] = *(const LAS bf16x8*)(lds + PG8_SA(b, h) + aoff + m * 2048 + k * 1024); } while (0)
; #define PG8_MMA(ai, bj, At, Bt) do { __builtin_amdgcn_s_setprio(1); _Pragma("unroll") for (int m = 0; m < 4; ++m) _Pragma("unroll") for (int n = 0; n < 2; ++n) _Pragma("unroll") for (int k = 0; k < 2; ++k) \
;         acc[ai][bj][m][n] = __builtin_amdgcn_mfma_f32_16x16x32_bf16(Bt[n][k], At[m][k], acc[ai][bj][m][n], 0, 0, 0); __builtin_amdgcn_s_setprio(0); } while (0)
; #define PG8_WAIT_V(n) asm volatile("s_waitcnt vmcnt(" #n ")" ::: "memory")
; #define PG8_WAIT_L(n) asm volatile("s_waitcnt lgkmcnt(" #n ")" ::: "memory")
; #define PG8_BAR __builtin_amdgcn_s_barrier()
; #define PG8_SCHED __builtin_amdgcn_sched_barrier(0)
; template <class Epi, class Sched>
; DI void gemm_phase(LAS unsigned char* lds, const int K, const Sched& S, const Epi& E) {
;     ...
;             PG8_LDA(At, 1, 1); PG8_STAGE(PG8_SB(1, 0), b3, voffB); PG8_STAGE(PG8_SB(1, 1), b3 + hstep, voffB); PG8_STAGE(PG8_SA(1, 0), a3, voffA);
;             PG8_WAIT_V(8); PG8_WAIT_L(0); PG8_BAR; PG8_MMA(1, 0, At, B0); PG8_MMA(1, 1, At, B1); PG8_BAR; PG8_SCHED;
;         }
;         if (wr == 0) PG8_BAR;
	s_add_i32 s48, s48, s79
	s_add_u32 s72, s72, 0x80
	s_addc_u32 s73, s73, 0
	s_mov_b32 m0, s48
	ds_read_b128 v[174:177], v200 offset:49152
	ds_read_b128 v[182:185], v200 offset:50176
	ds_read_b128 v[190:193], v200 offset:51200
	ds_read_b128 v[194:197], v200 offset:52224
	ds_read_b128 v[202:205], v200 offset:53248
	ds_read_b128 v[212:215], v200 offset:54272
	ds_read_b128 v[216:219], v200 offset:55296
	ds_read_b128 v[220:223], v200 offset:56320
	global_load_lds_dwordx4 v164, s[72:73]
	s_add_i32 m0, s48, 0x2000
	s_nop 0
	s_nop 0
	s_nop 0
	s_add_i32 s48, s49, s79
	global_load_lds_dwordx4 v168, s[72:73]
	s_add_u32 s72, s72, 0x40000
	s_addc_u32 s73, s73, 0
	s_nop 0
	s_mov_b32 m0, s48
	s_nop 0
	global_load_lds_dwordx4 v164, s[72:73]
	s_nop 0
	s_add_i32 m0, s48, 0x2000
	s_nop 0
	global_load_lds_dwordx4 v168, s[72:73]
	s_nop 0
	s_mov_b32 m0, s94
	s_nop 0
	global_load_lds_dwordx4 v162, s[98:99]
	s_nop 0
	s_mov_b32 m0, s95
	s_nop 0
	global_load_lds_dwordx4 v166, s[98:99]
	s_waitcnt vmcnt(8)
	s_waitcnt lgkmcnt(0)
	s_barrier
	s_nop 0
	s_waitcnt lgkmcnt(0)
	v_mfma_f32_16x16x32_bf16 v[62:65], v[130:133], v[174:177], v[62:65]
	v_mfma_f32_16x16x32_bf16 v[58:61], v[138:141], v[174:177], v[58:61]
	v_mfma_f32_16x16x32_bf16 v[54:57], v[130:133], v[190:193], v[54:57]
	v_mfma_f32_16x16x32_bf16 v[50:53], v[138:141], v[190:193], v[50:53]
	v_mfma_f32_16x16x32_bf16 v[46:49], v[130:133], v[202:205], v[46:49]
	v_mfma_f32_16x16x32_bf16 v[42:45], v[138:141], v[202:205], v[42:45]
	v_mfma_f32_16x16x32_bf16 v[38:41], v[130:133], v[216:219], v[38:41]
	v_mfma_f32_16x16x32_bf16 v[34:37], v[138:141], v[216:219], v[34:37]
	v_mfma_f32_16x16x32_bf16 v[62:65], v[134:137], v[182:185], v[62:65]
	v_mfma_f32_16x16x32_bf16 v[58:61], v[142:145], v[182:185], v[58:61]
	v_mfma_f32_16x16x32_bf16 v[54:57], v[134:137], v[194:197], v[54:57]
	v_mfma_f32_16x16x32_bf16 v[50:53], v[142:145], v[194:197], v[50:53]
	v_mfma_f32_16x16x32_bf16 v[46:49], v[134:137], v[212:215], v[46:49]
	v_mfma_f32_16x16x32_bf16 v[42:45], v[142:145], v[212:215], v[42:45]
	v_mfma_f32_16x16x32_bf16 v[38:41], v[134:137], v[220:223], v[38:41]
	v_mfma_f32_16x16x32_bf16 v[34:37], v[142:145], v[220:223], v[34:37]
	s_nop 0
	s_nop 0
	v_mfma_f32_16x16x32_bf16 v[30:33], v[146:149], v[174:177], v[30:33]
	v_mfma_f32_16x16x32_bf16 v[26:29], v[154:157], v[174:177], v[26:29]
	v_mfma_f32_16x16x32_bf16 v[22:25], v[146:149], v[190:193], v[22:25]
	v_mfma_f32_16x16x32_bf16 v[18:21], v[154:157], v[190:193], v[18:21]
	v_mfma_f32_16x16x32_bf16 v[14:17], v[146:149], v[202:205], v[14:17]
	v_mfma_f32_16x16x32_bf16 v[10:13], v[154:157], v[202:205], v[10:13]
	v_mfma_f32_16x16x32_bf16 v[6:9], v[146:149], v[216:219], v[6:9]
	v_mfma_f32_16x16x32_bf16 v[2:5], v[154:157], v[216:219], v[2:5]
	v_mfma_f32_16x16x32_bf16 v[30:33], v[150:153], v[182:185], v[30:33]
	v_mfma_f32_16x16x32_bf16 v[26:29], v[158:161], v[182:185], v[26:29]
	v_mfma_f32_16x16x32_bf16 v[22:25], v[150:153], v[194:197], v[22:25]
	v_mfma_f32_16x16x32_bf16 v[18:21], v[158:161], v[194:197], v[18:21]
	v_mfma_f32_16x16x32_bf16 v[14:17], v[150:153], v[212:215], v[14:17]
	v_mfma_f32_16x16x32_bf16 v[10:13], v[158:161], v[212:215], v[10:13]
	v_mfma_f32_16x16x32_bf16 v[6:9], v[150:153], v[220:223], v[6:9]
	v_mfma_f32_16x16x32_bf16 v[2:5], v[158:161], v[220:223], v[2:5]
	s_nop 0
	s_barrier
	s_add_i32 s76, s76, 2
	s_add_u32 s65, s65, 0x100
	s_addc_u32 s67, s67, 0
	s_add_u32 s44, s44, 0x100
	s_addc_u32 s45, s45, 0
	s_cmp_gt_u32 s76, 13
	s_cbranch_scc0 .LBB0_784
	s_and_b64 vcc, exec, s[58:59]
	s_cbranch_vccz .LBB0_787
	s_barrier

; #define PG8_STAGE(bufoff, gbase, voff) do { _Pragma("unroll") for (int _i = 0; _i < 2; ++_i) \
;         __builtin_amdgcn_global_load_lds((const unsigned*)((const char*)(gbase) + (voff)[_i]), (LAS unsigned*)(lds + (bufoff) + ldsw + _i * 8192), 16, 0, 0); } while (0)
; #define PG8_LDA(dst, b, h) do { _Pragma("unroll") for (int m = 0; m < 4; ++m) _Pragma("unroll") for (int k = 0; k < 2; ++k) dst[m][k] = *(const LAS bf16x8*)(lds + PG8_SA(b, h) + aoff + m * 2048 + k * 1024); } while (0)
; #define PG8_LDB(dst, b, h) do { _Pragma("unroll") for (int n = 0; n < 2; ++n) _Pragma("unroll") for (int k = 0; k < 2; ++k) dst[n][k] = *(const LAS bf16x8*)(lds + PG8_SB(b, h) + boff + n * 2048 + k * 1024); } while (0)
; #define PG8_MMA(ai, bj, At, Bt) do { __builtin_amdgcn_s_setprio(1); _Pragma("unroll") for (int m = 0; m < 4; ++m) _Pragma("unroll") for (int n = 0; n < 2; ++n) _Pragma("unroll") for (int k = 0; k < 2; ++k) \
;         acc[ai][bj][m][n] = __builtin_amdgcn_mfma_f32_16x16x32_bf16(Bt[n][k], At[m][k], acc[ai][bj][m][n], 0, 0, 0); __builtin_amdgcn_s_setprio(0); } while (0)
; #define PG8_WAIT_V(n) asm volatile("s_waitcnt vmcnt(" #n ")" ::: "memory")
; #define PG8_WAIT_L(n) asm volatile("s_waitcnt lgkmcnt(" #n ")" ::: "memory")
; #define PG8_BAR __builtin_amdgcn_s_barrier()
; #define PG8_SCHED __builtin_amdgcn_sched_barrier(0)
; template <class Epi, class Sched>
; DI void gemm_phase(LAS unsigned char* lds, const int K, const Sched& S, const Epi& E) {
;     ...
;             const bool last = (t == nt - 2);
;             const char* a1 = cA + (size_t)(t + 1) * kstep;
;             const char* a2 = last ? nA : cA + (size_t)(t + 2) * kstep; const char* b2 = last ? nB : cB + (size_t)(t + 2) * kstep;
;             const char* a3 = a2 + kstep; const char* b3 = b2 + kstep;
;             PG8_LDB(B0, 0, 0); PG8_LDB(B1, 0, 1); PG8_SCHED; PG8_LDA(At, 0, 0); PG8_STAGE(PG8_SA(1, 1), a1 + hstep, voffA);
;             PG8_WAIT_V(8); PG8_WAIT_L(0); PG8_BAR; PG8_MMA(0, 0, At, B0); PG8_MMA(0, 1, At, B1); PG8_BAR; PG8_SCHED;
;             PG8_LDA(At, 0, 1); PG8_STAGE(PG8_SB(0, 0), b2, voffB); PG8_STAGE(PG8_SB(0, 1), b2 + hstep, voffB); PG8_STAGE(PG8_SA(0, 0), a2, voffA);
;             PG8_WAIT_V(8); PG8_WAIT_L(0); PG8_BAR; PG8_MMA(1, 0, At, B0); PG8_MMA(1, 1, At, B1); PG8_BAR; PG8_SCHED;
.LBB0_945:
	s_add_u32 s48, s62, 0xfffc0080
	s_addc_u32 s49, s63, -1
	s_add_i32 s84, 0, 0x10000
	s_cmp_eq_u32 s83, 12
	s_cselect_b32 s67, s59, s49
	s_cselect_b32 s66, s58, s48
	v_add_u32_e32 v145, s84, v143
	s_cselect_b32 s65, s61, s57
	s_cselect_b32 s64, s60, s55
	s_add_i32 s48, 0, 0x14000
	ds_read_b128 v[146:149], v145
	ds_read_b128 v[150:153], v145 offset:1024
	ds_read_b128 v[154:157], v145 offset:2048
	ds_read_b128 v[158:161], v145 offset:3072
	v_add_u32_e32 v145, s48, v143
	ds_read_b128 v[162:165], v145
	ds_read_b128 v[166:169], v145 offset:1024
	ds_read_b128 v[170:173], v145 offset:2048
	ds_read_b128 v[174:177], v145 offset:3072
	s_nop 0
	s_add_i32 m0, s53, 0xc000
	ds_read_b128 v[182:185], v144
	ds_read_b128 v[190:193], v144 offset:1024
	ds_read_b128 v[194:197], v144 offset:2048
	ds_read_b128 v[198:201], v144 offset:3072
	ds_read_b128 v[202:205], v144 offset:4096
	ds_read_b128 v[212:215], v144 offset:5120
	ds_read_b128 v[216:219], v144 offset:6144
	ds_read_b128 v[220:223], v144 offset:7168
	global_load_lds_dwordx4 v140, s[62:63]
	s_nop 0
	s_add_i32 m0, s53, 0xe000
	s_nop 0
	global_load_lds_dwordx4 v138, s[62:63]
	s_waitcnt vmcnt(8)
	s_waitcnt lgkmcnt(0)
	s_barrier
	s_nop 0
	s_waitcnt lgkmcnt(0)
	v_mfma_f32_16x16x32_bf16 v[126:129], v[146:149], v[182:185], v[126:129]
	v_mfma_f32_16x16x32_bf16 v[122:125], v[154:157], v[182:185], v[122:125]
	v_mfma_f32_16x16x32_bf16 v[118:121], v[146:149], v[194:197], v[118:121]
	v_mfma_f32_16x16x32_bf16 v[114:117], v[154:157], v[194:197], v[114:117]
	v_mfma_f32_16x16x32_bf16 v[102:105], v[146:149], v[202:205], v[102:105]
	v_mfma_f32_16x16x32_bf16 v[98:101], v[154:157], v[202:205], v[98:101]
	v_mfma_f32_16x16x32_bf16 v[86:89], v[146:149], v[216:219], v[86:89]
	v_mfma_f32_16x16x32_bf16 v[82:85], v[154:157], v[216:219], v[82:85]
	v_mfma_f32_16x16x32_bf16 v[126:129], v[150:153], v[190:193], v[126:129]
	v_mfma_f32_16x16x32_bf16 v[122:125], v[158:161], v[190:193], v[122:125]
	v_mfma_f32_16x16x32_bf16 v[118:121], v[150:153], v[198:201], v[118:121]
	v_mfma_f32_16x16x32_bf16 v[114:117], v[158:161], v[198:201], v[114:117]
	v_mfma_f32_16x16x32_bf16 v[102:105], v[150:153], v[212:215], v[102:105]
	v_mfma_f32_16x16x32_bf16 v[98:101], v[158:161], v[212:215], v[98:101]
	v_mfma_f32_16x16x32_bf16 v[86:89], v[150:153], v[220:223], v[86:89]
	v_mfma_f32_16x16x32_bf16 v[82:85], v[158:161], v[220:223], v[82:85]
	s_nop 0
	s_nop 0
	v_mfma_f32_16x16x32_bf16 v[110:113], v[162:165], v[182:185], v[110:113]
	v_mfma_f32_16x16x32_bf16 v[106:109], v[170:173], v[182:185], v[106:109]
	v_mfma_f32_16x16x32_bf16 v[94:97], v[162:165], v[194:197], v[94:97]
	v_mfma_f32_16x16x32_bf16 v[90:93], v[170:173], v[194:197], v[90:93]
	v_mfma_f32_16x16x32_bf16 v[78:81], v[162:165], v[202:205], v[78:81]
	v_mfma_f32_16x16x32_bf16 v[74:77], v[170:173], v[202:205], v[74:77]
	v_mfma_f32_16x16x32_bf16 v[70:73], v[162:165], v[216:219], v[70:73]
	v_mfma_f32_16x16x32_bf16 v[66:69], v[170:173], v[216:219], v[66:69]
	v_mfma_f32_16x16x32_bf16 v[110:113], v[166:169], v[190:193], v[110:113]
	v_mfma_f32_16x16x32_bf16 v[106:109], v[174:177], v[190:193], v[106:109]
	v_mfma_f32_16x16x32_bf16 v[94:97], v[166:169], v[198:201], v[94:97]
	v_mfma_f32_16x16x32_bf16 v[90:93], v[174:177], v[198:201], v[90:93]
	v_mfma_f32_16x16x32_bf16 v[78:81], v[166:169], v[212:215], v[78:81]
	v_mfma_f32_16x16x32_bf16 v[74:77], v[174:177], v[212:215], v[74:77]
	v_mfma_f32_16x16x32_bf16 v[70:73], v[166:169], v[220:223], v[70:73]
	v_mfma_f32_16x16x32_bf16 v[66:69], v[174:177], v[220:223], v[66:69]
	s_nop 0
	s_barrier
	s_add_i32 s49, s84, s71
	s_nop 0
	s_mov_b32 m0, s49
	ds_read_b128 v[182:185], v144 offset:16384
	ds_read_b128 v[190:193], v144 offset:17408
	ds_read_b128 v[194:197], v144 offset:18432
	ds_read_b128 v[198:201], v144 offset:19456
	ds_read_b128 v[202:205], v144 offset:20480
	ds_read_b128 v[212:215], v144 offset:21504
	ds_read_b128 v[216:219], v144 offset:22528
	ds_read_b128 v[220:223], v144 offset:23552
	global_load_lds_dwordx4 v134, s[64:65]
	s_add_i32 m0, s49, 0x2000
	s_add_u32 s84, s64, 0x40000
	s_nop 0
	s_addc_u32 s85, s65, 0
	s_add_i32 s48, s48, s71
	global_load_lds_dwordx4 v130, s[64:65]
	s_nop 0
	s_mov_b32 m0, s48
	s_nop 0
	global_load_lds_dwordx4 v134, s[84:85]
	s_nop 0
	s_add_i32 m0, s48, 0x2000
	s_nop 0
	global_load_lds_dwordx4 v130, s[84:85]
	s_nop 0
	s_add_u32 s98, s66, s90
	s_addc_u32 s99, s67, s91
	s_mov_b32 m0, s53
	s_nop 0
	global_load_lds_dwordx4 v136, s[66:67]
	s_mov_b32 m0, s73
	s_nop 0
	global_load_lds_dwordx4 v132, s[66:67]
	s_waitcnt vmcnt(8)
	s_waitcnt lgkmcnt(0)
	s_barrier
; #define PG8_STAGE(bufoff, gbase, voff) do { _Pragma("unroll") for (int _i = 0; _i < 2; ++_i) \
;         __builtin_amdgcn_global_load_lds((const unsigned*)((const char*)(gbase) + (voff)[_i]), (LAS unsigned*)(lds + (bufoff) + ldsw + _i * 8192), 16, 0, 0); } while (0)
; #define PG8_LDA(dst, b, h) do { _Pragma("unroll") for (int m = 0; m < 4; ++m) _Pragma("unroll") for (int k = 0; k < 2; ++k) dst[m][k] = *(const LAS bf16x8*)(lds + PG8_SA(b, h) + aoff + m * 2048 + k * 1024); } while (0)
; #define PG8_LDB(dst, b, h) do { _Pragma("unroll") for (int n = 0; n < 2; ++n) _Pragma("unroll") for (int k = 0; k < 2; ++k) dst[n][k] = *(const LAS bf16x8*)(lds + PG8_SB(b, h) + boff + n * 2048 + k * 1024); } while (0)
; #define PG8_MMA(ai, bj, At, Bt) do { __builtin_amdgcn_s_setprio(1); _Pragma("unroll") for (int m = 0; m < 4; ++m) _Pragma("unroll") for (int n = 0; n < 2; ++n) _Pragma("unroll") for (int k = 0; k < 2; ++k) \
;         acc[ai][bj][m][n] = __builtin_amdgcn_mfma_f32_16x16x32_bf16(Bt[n][k], At[m][k], acc[ai][bj][m][n], 0, 0, 0); __builtin_amdgcn_s_setprio(0); } while (0)
; #define PG8_WAIT_V(n) asm volatile("s_waitcnt vmcnt(" #n ")" ::: "memory")
; #define PG8_WAIT_L(n) asm volatile("s_waitcnt lgkmcnt(" #n ")" ::: "memory")
; #define PG8_BAR __builtin_amdgcn_s_barrier()
; #define PG8_SCHED __builtin_amdgcn_sched_barrier(0)
; template <class Epi, class Sched>
; DI void gemm_phase(LAS unsigned char* lds, const int K, const Sched& S, const Epi& E) {
;     ...
;             PG8_WAIT_V(8); PG8_WAIT_L(0); PG8_BAR; PG8_MMA(1, 0, At, B0); PG8_MMA(1, 1, At, B1); PG8_BAR; PG8_SCHED;
;             PG8_LDB(B0, 1, 0); PG8_LDB(B1, 1, 1); PG8_SCHED; PG8_LDA(At, 1, 0); PG8_STAGE(PG8_SA(0, 1), a2 + hstep, voffA);
;             PG8_WAIT_V(8); PG8_WAIT_L(0); PG8_BAR; PG8_MMA(0, 0, At, B0); PG8_MMA(0, 1, At, B1); PG8_BAR; PG8_SCHED;
	s_nop 0
	s_waitcnt lgkmcnt(0)
	v_mfma_f32_16x16x32_bf16 v[62:65], v[146:149], v[182:185], v[62:65]
	v_mfma_f32_16x16x32_bf16 v[58:61], v[154:157], v[182:185], v[58:61]
	v_mfma_f32_16x16x32_bf16 v[54:57], v[146:149], v[194:197], v[54:57]
	v_mfma_f32_16x16x32_bf16 v[50:53], v[154:157], v[194:197], v[50:53]
	v_mfma_f32_16x16x32_bf16 v[38:41], v[146:149], v[202:205], v[38:41]
	v_mfma_f32_16x16x32_bf16 v[34:37], v[154:157], v[202:205], v[34:37]
	v_mfma_f32_16x16x32_bf16 v[22:25], v[146:149], v[216:219], v[22:25]
	v_mfma_f32_16x16x32_bf16 v[18:21], v[154:157], v[216:219], v[18:21]
	v_mfma_f32_16x16x32_bf16 v[62:65], v[150:153], v[190:193], v[62:65]
	v_mfma_f32_16x16x32_bf16 v[58:61], v[158:161], v[190:193], v[58:61]
	v_mfma_f32_16x16x32_bf16 v[54:57], v[150:153], v[198:201], v[54:57]
	v_mfma_f32_16x16x32_bf16 v[50:53], v[158:161], v[198:201], v[50:53]
	v_mfma_f32_16x16x32_bf16 v[38:41], v[150:153], v[212:215], v[38:41]
	v_mfma_f32_16x16x32_bf16 v[34:37], v[158:161], v[212:215], v[34:37]
	v_mfma_f32_16x16x32_bf16 v[22:25], v[150:153], v[220:223], v[22:25]
	v_mfma_f32_16x16x32_bf16 v[18:21], v[158:161], v[220:223], v[18:21]
	s_nop 0
	s_nop 0
	v_mfma_f32_16x16x32_bf16 v[46:49], v[162:165], v[182:185], v[46:49]
	v_mfma_f32_16x16x32_bf16 v[42:45], v[170:173], v[182:185], v[42:45]
	v_mfma_f32_16x16x32_bf16 v[30:33], v[162:165], v[194:197], v[30:33]
	v_mfma_f32_16x16x32_bf16 v[26:29], v[170:173], v[194:197], v[26:29]
	v_mfma_f32_16x16x32_bf16 v[14:17], v[162:165], v[202:205], v[14:17]
	v_mfma_f32_16x16x32_bf16 v[10:13], v[170:173], v[202:205], v[10:13]
	v_mfma_f32_16x16x32_bf16 v[6:9], v[162:165], v[216:219], v[6:9]
	v_mfma_f32_16x16x32_bf16 v[2:5], v[170:173], v[216:219], v[2:5]
	v_mfma_f32_16x16x32_bf16 v[46:49], v[166:169], v[190:193], v[46:49]
	v_mfma_f32_16x16x32_bf16 v[42:45], v[174:177], v[190:193], v[42:45]
	v_mfma_f32_16x16x32_bf16 v[30:33], v[166:169], v[198:201], v[30:33]
	v_mfma_f32_16x16x32_bf16 v[26:29], v[174:177], v[198:201], v[26:29]
	v_mfma_f32_16x16x32_bf16 v[14:17], v[166:169], v[212:215], v[14:17]
	v_mfma_f32_16x16x32_bf16 v[10:13], v[174:177], v[212:215], v[10:13]
	v_mfma_f32_16x16x32_bf16 v[6:9], v[166:169], v[220:223], v[6:9]
	v_mfma_f32_16x16x32_bf16 v[2:5], v[174:177], v[220:223], v[2:5]
	s_nop 0
	s_barrier
	s_add_i32 s48, 0, 0x18000
	v_add_u32_e32 v145, s48, v143
	s_add_i32 s49, 0, 0x1c000
	ds_read_b128 v[146:149], v145
	ds_read_b128 v[150:153], v145 offset:1024
	ds_read_b128 v[154:157], v145 offset:2048
	ds_read_b128 v[158:161], v145 offset:3072
	v_add_u32_e32 v145, s49, v143
	ds_read_b128 v[162:165], v145
	ds_read_b128 v[166:169], v145 offset:1024
	ds_read_b128 v[170:173], v145 offset:2048
	ds_read_b128 v[174:177], v145 offset:3072
	s_add_u32 s66, s66, 0x40000
	s_addc_u32 s67, s67, 0
	s_mov_b32 m0, s74
	s_nop 0
	ds_read_b128 v[182:185], v144 offset:32768
	ds_read_b128 v[190:193], v144 offset:33792
	ds_read_b128 v[194:197], v144 offset:34816
	ds_read_b128 v[198:201], v144 offset:35840
	ds_read_b128 v[202:205], v144 offset:36864
	ds_read_b128 v[212:215], v144 offset:37888
	ds_read_b128 v[216:219], v144 offset:38912
	ds_read_b128 v[220:223], v144 offset:39936
	global_load_lds_dwordx4 v136, s[66:67]
	s_nop 0
	s_mov_b32 m0, s75
	s_nop 0
	global_load_lds_dwordx4 v132, s[66:67]
	s_waitcnt vmcnt(8)
	s_waitcnt lgkmcnt(0)
	s_barrier
	s_nop 0
	s_waitcnt lgkmcnt(0)
	v_mfma_f32_16x16x32_bf16 v[126:129], v[146:149], v[182:185], v[126:129]
	v_mfma_f32_16x16x32_bf16 v[122:125], v[154:157], v[182:185], v[122:125]
	v_mfma_f32_16x16x32_bf16 v[118:121], v[146:149], v[194:197], v[118:121]
	v_mfma_f32_16x16x32_bf16 v[114:117], v[154:157], v[194:197], v[114:117]
	v_mfma_f32_16x16x32_bf16 v[102:105], v[146:149], v[202:205], v[102:105]
	v_mfma_f32_16x16x32_bf16 v[98:101], v[154:157], v[202:205], v[98:101]
	v_mfma_f32_16x16x32_bf16 v[86:89], v[146:149], v[216:219], v[86:89]
	v_mfma_f32_16x16x32_bf16 v[82:85], v[154:157], v[216:219], v[82:85]
	v_mfma_f32_16x16x32_bf16 v[126:129], v[150:153], v[190:193], v[126:129]
	v_mfma_f32_16x16x32_bf16 v[122:125], v[158:161], v[190:193], v[122:125]
	v_mfma_f32_16x16x32_bf16 v[118:121], v[150:153], v[198:201], v[118:121]
	v_mfma_f32_16x16x32_bf16 v[114:117], v[158:161], v[198:201], v[114:117]
	v_mfma_f32_16x16x32_bf16 v[102:105], v[150:153], v[212:215], v[102:105]
	v_mfma_f32_16x16x32_bf16 v[98:101], v[158:161], v[212:215], v[98:101]
	v_mfma_f32_16x16x32_bf16 v[86:89], v[150:153], v[220:223], v[86:89]
	v_mfma_f32_16x16x32_bf16 v[82:85], v[158:161], v[220:223], v[82:85]
	s_nop 0
	s_nop 0
	v_mfma_f32_16x16x32_bf16 v[110:113], v[162:165], v[182:185], v[110:113]
	v_mfma_f32_16x16x32_bf16 v[106:109], v[170:173], v[182:185], v[106:109]
	v_mfma_f32_16x16x32_bf16 v[94:97], v[162:165], v[194:197], v[94:97]
	v_mfma_f32_16x16x32_bf16 v[90:93], v[170:173], v[194:197], v[90:93]
	v_mfma_f32_16x16x32_bf16 v[78:81], v[162:165], v[202:205], v[78:81]
	v_mfma_f32_16x16x32_bf16 v[74:77], v[170:173], v[202:205], v[74:77]
	v_mfma_f32_16x16x32_bf16 v[70:73], v[162:165], v[216:219], v[70:73]
	v_mfma_f32_16x16x32_bf16 v[66:69], v[170:173], v[216:219], v[66:69]
	v_mfma_f32_16x16x32_bf16 v[110:113], v[166:169], v[190:193], v[110:113]
	v_mfma_f32_16x16x32_bf16 v[106:109], v[174:177], v[190:193], v[106:109]
	v_mfma_f32_16x16x32_bf16 v[94:97], v[166:169], v[198:201], v[94:97]
	v_mfma_f32_16x16x32_bf16 v[90:93], v[174:177], v[198:201], v[90:93]
	v_mfma_f32_16x16x32_bf16 v[78:81], v[166:169], v[212:215], v[78:81]
	v_mfma_f32_16x16x32_bf16 v[74:77], v[174:177], v[212:215], v[74:77]
	v_mfma_f32_16x16x32_bf16 v[70:73], v[166:169], v[220:223], v[70:73]
	v_mfma_f32_16x16x32_bf16 v[66:69], v[174:177], v[220:223], v[66:69]
	s_nop 0
	s_barrier
; #define PG8_STAGE(bufoff, gbase, voff) do { _Pragma("unroll") for (int _i = 0; _i < 2; ++_i) \
;         __builtin_amdgcn_global_load_lds((const unsigned*)((const char*)(gbase) + (voff)[_i]), (LAS unsigned*)(lds + (bufoff) + ldsw + _i * 8192), 16, 0, 0); } while (0)
; #define PG8_LDA(dst, b, h) do { _Pragma("unroll") for (int m = 0; m < 4; ++m) _Pragma("unroll") for (int k = 0; k < 2; ++k) dst[m][k] = *(const LAS bf16x8*)(lds + PG8_SA(b, h) + aoff + m * 2048 + k * 1024); } while (0)
; #define PG8_MMA(ai, bj, At, Bt) do { __builtin_amdgcn_s_setprio(1); _Pragma("unroll") for (int m = 0; m < 4; ++m) _Pragma("unroll") for (int n = 0; n < 2; ++n) _Pragma("unroll") for (int k = 0; k < 2; ++k) \
;         acc[ai][bj][m][n] = __builtin_amdgcn_mfma_f32_16x16x32_bf16(Bt[n][k], At[m][k], acc[ai][bj][m][n], 0, 0, 0); __builtin_amdgcn_s_setprio(0); } while (0)
; #define PG8_WAIT_V(n) asm volatile("s_waitcnt vmcnt(" #n ")" ::: "memory")
; #define PG8_WAIT_L(n) asm volatile("s_waitcnt lgkmcnt(" #n ")" ::: "memory")
; #define PG8_BAR __builtin_amdgcn_s_barrier()
; #define PG8_SCHED __builtin_amdgcn_sched_barrier(0)
; template <class Epi, class Sched>
; DI void gemm_phase(LAS unsigned char* lds, const int K, const Sched& S, const Epi& E) {
;     ...
;             PG8_LDA(At, 1, 1); PG8_STAGE(PG8_SB(1, 0), b3, voffB); PG8_STAGE(PG8_SB(1, 1), b3 + hstep, voffB); PG8_STAGE(PG8_SA(1, 0), a3, voffA);
;             PG8_WAIT_V(8); PG8_WAIT_L(0); PG8_BAR; PG8_MMA(1, 0, At, B0); PG8_MMA(1, 1, At, B1); PG8_BAR; PG8_SCHED;
;         }
;         if (wr == 0) PG8_BAR;
	s_add_i32 s48, s48, s71
	s_add_u32 s64, s64, 0x80
	s_addc_u32 s65, s65, 0
	s_mov_b32 m0, s48
	ds_read_b128 v[182:185], v144 offset:49152
	ds_read_b128 v[190:193], v144 offset:50176
	ds_read_b128 v[194:197], v144 offset:51200
	ds_read_b128 v[198:201], v144 offset:52224
	ds_read_b128 v[202:205], v144 offset:53248
	ds_read_b128 v[212:215], v144 offset:54272
	ds_read_b128 v[216:219], v144 offset:55296
	ds_read_b128 v[220:223], v144 offset:56320
	global_load_lds_dwordx4 v134, s[64:65]
	s_add_i32 m0, s48, 0x2000
	s_nop 0
	s_nop 0
	s_nop 0
	s_add_i32 s48, s49, s71
	global_load_lds_dwordx4 v130, s[64:65]
	s_add_u32 s64, s64, 0x40000
	s_addc_u32 s65, s65, 0
	s_nop 0
	s_mov_b32 m0, s48
	s_nop 0
	global_load_lds_dwordx4 v134, s[64:65]
	s_nop 0
	s_add_i32 m0, s48, 0x2000
	s_nop 0
	global_load_lds_dwordx4 v130, s[64:65]
	s_nop 0
	s_mov_b32 m0, s78
	s_nop 0
	global_load_lds_dwordx4 v136, s[98:99]
	s_nop 0
	s_mov_b32 m0, s79
	s_nop 0
	global_load_lds_dwordx4 v132, s[98:99]
	s_waitcnt vmcnt(8)
	s_waitcnt lgkmcnt(0)
	s_barrier
	s_nop 0
	s_waitcnt lgkmcnt(0)
	v_mfma_f32_16x16x32_bf16 v[62:65], v[146:149], v[182:185], v[62:65]
	v_mfma_f32_16x16x32_bf16 v[58:61], v[154:157], v[182:185], v[58:61]
	v_mfma_f32_16x16x32_bf16 v[54:57], v[146:149], v[194:197], v[54:57]
	v_mfma_f32_16x16x32_bf16 v[50:53], v[154:157], v[194:197], v[50:53]
	v_mfma_f32_16x16x32_bf16 v[38:41], v[146:149], v[202:205], v[38:41]
	v_mfma_f32_16x16x32_bf16 v[34:37], v[154:157], v[202:205], v[34:37]
	v_mfma_f32_16x16x32_bf16 v[22:25], v[146:149], v[216:219], v[22:25]
	v_mfma_f32_16x16x32_bf16 v[18:21], v[154:157], v[216:219], v[18:21]
	v_mfma_f32_16x16x32_bf16 v[62:65], v[150:153], v[190:193], v[62:65]
	v_mfma_f32_16x16x32_bf16 v[58:61], v[158:161], v[190:193], v[58:61]
	v_mfma_f32_16x16x32_bf16 v[54:57], v[150:153], v[198:201], v[54:57]
	v_mfma_f32_16x16x32_bf16 v[50:53], v[158:161], v[198:201], v[50:53]
	v_mfma_f32_16x16x32_bf16 v[38:41], v[150:153], v[212:215], v[38:41]
	v_mfma_f32_16x16x32_bf16 v[34:37], v[158:161], v[212:215], v[34:37]
	v_mfma_f32_16x16x32_bf16 v[22:25], v[150:153], v[220:223], v[22:25]
	v_mfma_f32_16x16x32_bf16 v[18:21], v[158:161], v[220:223], v[18:21]
	s_nop 0
	s_nop 0
	v_mfma_f32_16x16x32_bf16 v[46:49], v[162:165], v[182:185], v[46:49]
	v_mfma_f32_16x16x32_bf16 v[42:45], v[170:173], v[182:185], v[42:45]
	v_mfma_f32_16x16x32_bf16 v[30:33], v[162:165], v[194:197], v[30:33]
	v_mfma_f32_16x16x32_bf16 v[26:29], v[170:173], v[194:197], v[26:29]
	v_mfma_f32_16x16x32_bf16 v[14:17], v[162:165], v[202:205], v[14:17]
	v_mfma_f32_16x16x32_bf16 v[10:13], v[170:173], v[202:205], v[10:13]
	v_mfma_f32_16x16x32_bf16 v[6:9], v[162:165], v[216:219], v[6:9]
	v_mfma_f32_16x16x32_bf16 v[2:5], v[170:173], v[216:219], v[2:5]
	v_mfma_f32_16x16x32_bf16 v[46:49], v[166:169], v[190:193], v[46:49]
	v_mfma_f32_16x16x32_bf16 v[42:45], v[174:177], v[190:193], v[42:45]
	v_mfma_f32_16x16x32_bf16 v[30:33], v[166:169], v[198:201], v[30:33]
	v_mfma_f32_16x16x32_bf16 v[26:29], v[174:177], v[198:201], v[26:29]
	v_mfma_f32_16x16x32_bf16 v[14:17], v[166:169], v[212:215], v[14:17]
	v_mfma_f32_16x16x32_bf16 v[10:13], v[174:177], v[212:215], v[10:13]
	v_mfma_f32_16x16x32_bf16 v[6:9], v[166:169], v[220:223], v[6:9]
	v_mfma_f32_16x16x32_bf16 v[2:5], v[174:177], v[220:223], v[2:5]
	s_nop 0
	s_barrier
	s_add_i32 s83, s83, 2
	s_add_u32 s55, s55, 0x100
	s_addc_u32 s57, s57, 0
	s_add_u32 s62, s62, 0x100
	s_addc_u32 s63, s63, 0
	s_cmp_gt_u32 s83, 13
	s_cbranch_scc0 .LBB0_945
	s_and_b64 vcc, exec, s[50:51]
	s_cbranch_vccz .LBB0_948
	s_barrier
